# v_permlane32_swap at three more lane^32 reductions of the NSA item (QK-norm sum, compressed-branch sum, selected-branch tail max)
# speedup vs baseline: 1.0019x; 1.0019x over previous
; DI void nsa_item(unsigned char* ws_, const float* qg, const bf16_t* proj, bf16_t* mix, int item, LP unsigned char* lds3) {
;     ...
;   const int tid = TIDX(), lane = tid & 63, wave = tid >> 6, r = lane & 31, hh = lane >> 5;
;   const int qt = 31 - (item >> 6), bg = item & 63, b = bg >> 2, g = bg & 3;
;   const int hd = wave & 3, th = wave >> 2, tl = th * 32 + r, t = qt * 64 + tl;
;   bf16_t* Ks = (bf16_t*)lds;
;   bf16_t* VTs = (bf16_t*)(lds + 18432);
;   float* imp = (float*)(lds + 35840);
;   unsigned* msk = (unsigned*)(lds + 68608);
;   float* cmb = (float*)(lds + 69632) + tid;
;   const size_t tokrow = (size_t)(b * 2048 + t) * LDP0;
;   bf16x8 qf[4];
;   {
;     float qv[4][8]; float ss = 0.f;
; #pragma unroll
;     for (int kk = 0; kk < 4; ++kk) { unpack8(*(const u32x4*)(proj + tokrow + N_Q + (g * 4 + hd) * 64 + kk * 16 + 8 * hh), qv[kk]);
; #pragma unroll
;       for (int e = 0; e < 8; ++e) ss += qv[kk][e] * qv[kk][e]; }
;     ss += __shfl_xor(ss, 32);
;     const float rstd = rsqrtf(ss * (1.f / 64.f) + EPS) * 0.18033688011112042f;
; #pragma unroll
;     for (int kk = 0; kk < 4; ++kk) { const f32x4 g0v = *(const f32x4*)(qg + kk * 16 + 8 * hh), g1v = *(const f32x4*)(qg + kk * 16 + 8 * hh + 4);
;       qf[kk] = pack8(qv[kk][0] * rstd * g0v[0], qv[kk][1] * rstd * g0v[1], qv[kk][2] * rstd * g0v[2], qv[kk][3] * rstd * g0v[3],
;                      qv[kk][4] * rstd * g1v[0], qv[kk][5] * rstd * g1v[1], qv[kk][6] * rstd * g1v[2], qv[kk][7] * rstd * g1v[3]); } }
;   const float g0 = sigmf(bf2f(proj[tokrow + N_GT + (g * 4 + hd) * 3 + 0]));
;   const float g1 = sigmf(bf2f(proj[tokrow + N_GT + (g * 4 + hd) * 3 + 1]));
;   const float g2 = sigmf(bf2f(proj[tokrow + N_GT + (g * 4 + hd) * 3 + 2]));
;   __syncthreads();
;   { const bf16_t* kc = (const bf16_t*)(p.ws + WS_KCMP) + (size_t)bg * 128 * 64; const bf16_t* vc = (const bf16_t*)(p.ws + WS_VCMP) + (size_t)bg * 64 * 128;
; #pragma unroll
;     for (int i = 0; i < 2; ++i) { const int idx = tid + 512 * i; { const int n = idx >> 3, c = idx & 7; *(u32x4*)(Ks + n * 72 + c * 8) = *(const u32x4*)(kc + n * 64 + c * 8); }
;       { const int dd = idx >> 4, c = idx & 15; *(u32x4*)(VTs + dd * 136 + c * 8) = *(const u32x4*)(vc + dd * 128 + c * 8); } } }
; __global__ void __launch_bounds__(512, 2) fwd_mega(Params p_unused) {
;     ...
;         __syncthreads();
;         if (TIDX() == 0) s_item = (int)atomicAdd(qctr, 1u);
.LBB0_395:
	s_or_b64 exec, exec, s[2:3]
	s_mov_b64 s[2:3], src_shared_base
	v_mov_b32_e32 v171, s3
	s_waitcnt lgkmcnt(0)
	s_barrier
	flat_load_dword v3, v[170:171] sc0 sc1
	s_waitcnt vmcnt(0)
	s_movk_i32 s2, 0x880
	s_waitcnt lgkmcnt(0)
	v_cmp_gt_i32_e32 vcc, s2, v3
	s_mov_b64 s[2:3], -1
	s_mov_b64 s[4:5], exec
	v_writelane_b32 v252, s4, 52
	s_nop 1
	v_writelane_b32 v252, s5, 53
	s_and_b64 s[4:5], s[4:5], vcc
	s_mov_b64 exec, s[4:5]
	s_cbranch_execz .LBB0_390
	s_movk_i32 s2, 0x7f
	v_cmp_lt_i32_e32 vcc, s2, v3
	s_and_saveexec_b64 s[2:3], vcc
	s_xor_b64 s[2:3], exec, s[2:3]
	v_writelane_b32 v252, s2, 54
	s_nop 1
	v_writelane_b32 v252, s3, 55
	s_cbranch_execz .LBB0_645
	v_readlane_b32 s2, v252, 38
	v_add_u32_e32 v86, 0xffffff80, v3
	v_readlane_b32 s3, v252, 39
	v_mov_b32_e32 v84, v185
	v_lshrrev_b32_e32 v108, 6, v86
	s_load_dwordx2 s[2:3], s[2:3], 0x78
	v_xor_b32_e32 v100, 31, v108
	v_ashrrev_i32_e32 v106, 3, v84
	s_movk_i32 s4, 0xffe0
	v_bfi_b32 v109, s4, v106, v84
	v_lshlrev_b32_e32 v110, 6, v100
	v_readlane_b32 s4, v252, 40
	v_bfe_u32 v85, v3, 2, 4
	v_add_u32_e32 v101, v109, v110
	v_readlane_b32 s5, v252, 41
	v_and_b32_e32 v107, 3, v3
	v_lshl_add_u32 v88, v85, 11, v101
	v_mov_b64_e32 v[0:1], s[4:5]
	v_bfe_u32 v91, v84, 6, 2
	v_mad_i64_i32 v[64:65], s[4:5], v88, s97, v[0:1]
	v_lshlrev_b32_e32 v0, 9, v107
	v_bfe_u32 v89, v84, 5, 1
	v_lshl_or_b32 v168, v91, 7, v0
	v_lshl_add_u64 v[0:1], v[64:65], 0, v[168:169]
	v_lshlrev_b32_e32 v32, 4, v89
	v_mov_b32_e32 v33, v169
	v_lshl_add_u64 v[0:1], v[0:1], 0, v[32:33]
	s_mov_b64 s[4:5], 0x1820
	v_lshl_add_u64 v[4:5], v[0:1], 0, s[4:5]
	s_movk_i32 s4, 0x1000
	v_add_co_u32_e32 v0, vcc, s4, v0
	global_load_dwordx4 v[42:45], v[4:5], off offset:96
	global_load_dwordx4 v[50:53], v[4:5], off offset:64
	global_load_dwordx4 v[58:61], v[4:5], off offset:32
	v_addc_co_u32_e32 v1, vcc, 0, v1, vcc
	global_load_dwordx4 v[70:73], v[0:1], off offset:2080
	v_and_b32_e32 v1, 64, v199
	v_xor_b32_e32 v0, 32, v199
	v_add_u32_e32 v1, 64, v1
	v_lshl_or_b32 v98, v107, 2, v91
	v_cmp_lt_i32_e32 vcc, v0, v1
	v_lshlrev_b32_e32 v20, 5, v89
	v_and_b32_e32 v33, 63, v3
	v_cndmask_b32_e32 v0, v199, v0, vcc
	v_lshlrev_b32_e32 v102, 2, v0
	s_waitcnt lgkmcnt(0)
	global_load_dwordx4 v[12:15], v20, s[2:3] offset:16
	global_load_dwordx4 v[28:31], v20, s[2:3]
	global_load_dwordx4 v[4:7], v20, s[2:3] offset:80
	global_load_dwordx4 v[8:11], v20, s[2:3] offset:64
	global_load_dwordx4 v[24:27], v20, s[2:3] offset:144
	global_load_dwordx4 v[0:3], v20, s[2:3] offset:128
	global_load_dwordx4 v[16:19], v20, s[2:3] offset:208
	s_nop 0
	global_load_dwordx4 v[20:23], v20, s[2:3] offset:192
	s_mov_b64 s[2:3], 0x2c20
	v_add_u32_e32 v103, 0x200, v84
	v_mov_b32_e32 v133, v169
	v_ashrrev_i32_e32 v111, 3, v103
	v_lshlrev_b32_e32 v78, 6, v111
	v_ashrrev_i32_e32 v79, 31, v78
	s_movk_i32 s4, 0x90
	s_movk_i32 s5, 0x110
	v_cmp_eq_u32_e64 s[6:7], 0, v89
	s_mov_b32 s90, 0xefa18f08
	s_waitcnt vmcnt(11)
	v_lshlrev_b32_e32 v34, 16, v45
	v_and_b32_e32 v35, 0xffff0000, v45
	v_lshlrev_b32_e32 v36, 16, v44
	v_and_b32_e32 v37, 0xffff0000, v44
	v_lshlrev_b32_e32 v38, 16, v43
	s_waitcnt vmcnt(8)
	v_lshlrev_b32_e32 v130, 16, v70
	v_and_b32_e32 v131, 0xffff0000, v70
	v_lshlrev_b32_e32 v62, 16, v71
	v_and_b32_e32 v63, 0xffff0000, v71
	v_pk_mul_f32 v[70:71], v[130:131], v[130:131]
	v_and_b32_e32 v39, 0xffff0000, v43
	v_lshlrev_b32_e32 v40, 16, v42
	v_and_b32_e32 v41, 0xffff0000, v42
	v_lshlrev_b32_e32 v42, 16, v53
	v_and_b32_e32 v43, 0xffff0000, v53
	v_lshlrev_b32_e32 v44, 16, v52
	v_and_b32_e32 v45, 0xffff0000, v52
	v_lshlrev_b32_e32 v46, 16, v51
	v_and_b32_e32 v47, 0xffff0000, v51
	v_lshlrev_b32_e32 v48, 16, v50
	v_and_b32_e32 v49, 0xffff0000, v50
	v_lshlrev_b32_e32 v50, 16, v61
	v_and_b32_e32 v51, 0xffff0000, v61
	v_lshlrev_b32_e32 v52, 16, v60
	v_and_b32_e32 v53, 0xffff0000, v60
	v_lshlrev_b32_e32 v54, 16, v59
	v_and_b32_e32 v55, 0xffff0000, v59
	v_lshlrev_b32_e32 v56, 16, v58
	v_and_b32_e32 v57, 0xffff0000, v58
	v_lshlrev_b32_e32 v58, 16, v73
	v_and_b32_e32 v59, 0xffff0000, v73
	v_lshlrev_b32_e32 v60, 16, v72
	v_and_b32_e32 v61, 0xffff0000, v72
	v_pk_mul_f32 v[72:73], v[62:63], v[62:63]
	v_add_f32_e32 v70, v70, v71
	v_add_f32_e32 v70, v72, v70
	v_pk_mul_f32 v[128:129], v[60:61], v[60:61]
	v_add_f32_e32 v70, v73, v70
	v_add_f32_e32 v90, v128, v70
	v_mul_u32_u24_e32 v70, 3, v98
	v_lshlrev_b32_e32 v168, 1, v70
	v_lshl_add_u64 v[64:65], v[64:65], 0, v[168:169]
	v_lshl_add_u64 v[70:71], v[64:65], 0, s[2:3]
	s_movk_i32 s2, 0x2000
	v_add_co_u32_e32 v64, vcc, s2, v64
	v_readlane_b32 s2, v252, 44
	s_nop 0
	v_addc_co_u32_e32 v65, vcc, 0, v65, vcc
	v_lshlrev_b32_e32 v168, 14, v33
	v_readlane_b32 s3, v252, 45
	global_load_dword v87, v[64:65], off offset:3104
	global_load_ushort v99, v[70:71], off offset:4
	v_lshl_add_u64 v[64:65], s[2:3], 0, v[168:169]
	v_readlane_b32 s2, v252, 48
	v_lshlrev_b32_e32 v33, 3, v84
	v_readlane_b32 s3, v252, 49
	v_and_b32_e32 v33, 56, v33
	v_ashrrev_i32_e32 v128, 4, v103
	v_lshl_add_u64 v[70:71], s[2:3], 0, v[168:169]
	v_lshlrev_b32_e32 v168, 1, v33
	v_lshlrev_b32_e32 v33, 4, v84
	v_and_b32_e32 v132, 0xf0, v33
	v_ashrrev_i32_e32 v33, 4, v84
	v_lshl_add_u64 v[112:113], v[70:71], 0, v[132:133]
	v_lshlrev_b32_e32 v70, 6, v106
	v_lshlrev_b32_e32 v72, 7, v33
	v_lshl_add_u64 v[64:65], v[64:65], 0, v[168:169]
	v_ashrrev_i32_e32 v71, 31, v70
	v_ashrrev_i32_e32 v73, 31, v72
	v_lshl_add_u64 v[70:71], v[70:71], 1, v[64:65]
	v_lshl_add_u64 v[74:75], v[72:73], 1, v[112:113]
	v_lshl_add_u64 v[64:65], v[78:79], 1, v[64:65]
	s_barrier
; DI float bf2f(bf16_t b) { return __uint_as_float(((unsigned)b) << 16); }
; DI float sigmf(float x) { return 1.f / (1.f + __expf(-x)); }
; #define MFMA32(a, b, c) __builtin_amdgcn_mfma_f32_32x32x16_bf16((a), (b), (c), 0, 0, 0)
; DI void nsa_item(unsigned char* ws_, const float* qg, const bf16_t* proj, bf16_t* mix, int item, LP unsigned char* lds3) {
;     ...
;   {
;     float qv[4][8]; float ss = 0.f;
; #pragma unroll
;     for (int kk = 0; kk < 4; ++kk) { unpack8(*(const u32x4*)(proj + tokrow + N_Q + (g * 4 + hd) * 64 + kk * 16 + 8 * hh), qv[kk]);
; #pragma unroll
;       for (int e = 0; e < 8; ++e) ss += qv[kk][e] * qv[kk][e]; }
;     ss += __shfl_xor(ss, 32);
;     const float rstd = rsqrtf(ss * (1.f / 64.f) + EPS) * 0.18033688011112042f;
; #pragma unroll
;     for (int kk = 0; kk < 4; ++kk) { const f32x4 g0v = *(const f32x4*)(qg + kk * 16 + 8 * hh), g1v = *(const f32x4*)(qg + kk * 16 + 8 * hh + 4);
;       qf[kk] = pack8(qv[kk][0] * rstd * g0v[0], qv[kk][1] * rstd * g0v[1], qv[kk][2] * rstd * g0v[2], qv[kk][3] * rstd * g0v[3],
;                      qv[kk][4] * rstd * g1v[0], qv[kk][5] * rstd * g1v[1], qv[kk][6] * rstd * g1v[2], qv[kk][7] * rstd * g1v[3]); } }
;   const float g0 = sigmf(bf2f(proj[tokrow + N_GT + (g * 4 + hd) * 3 + 0]));
;   const float g1 = sigmf(bf2f(proj[tokrow + N_GT + (g * 4 + hd) * 3 + 1]));
;   const float g2 = sigmf(bf2f(proj[tokrow + N_GT + (g * 4 + hd) * 3 + 2]));
;   __syncthreads();
;   { const bf16_t* kc = (const bf16_t*)(p.ws + WS_KCMP) + (size_t)bg * 128 * 64; const bf16_t* vc = (const bf16_t*)(p.ws + WS_VCMP) + (size_t)bg * 64 * 128;
; #pragma unroll
;     for (int i = 0; i < 2; ++i) { const int idx = tid + 512 * i; { const int n = idx >> 3, c = idx & 7; *(u32x4*)(Ks + n * 72 + c * 8) = *(const u32x4*)(kc + n * 64 + c * 8); }
;       { const int dd = idx >> 4, c = idx & 15; *(u32x4*)(VTs + dd * 136 + c * 8) = *(const u32x4*)(vc + dd * 128 + c * 8); } } }
;   __syncthreads();
;   {
;     f32x16 x[4]; float mx = NEGF;
; #pragma unroll
;     for (int sub = 0; sub < 4; ++sub) { x[sub] = zero16();
; #pragma unroll
;       for (int kk = 0; kk < 4; ++kk) x[sub] = MFMA32(*(const bf16x8*)(Ks + (sub * 32 + r) * 72 + kk * 16 + 8 * hh), qf[kk], x[sub]);
	global_load_dwordx4 v[70:73], v[70:71], off
	s_nop 0
	global_load_dwordx4 v[74:77], v[74:75], off
	v_pk_mul_f32 v[126:127], v[58:59], v[58:59]
	global_load_dwordx4 v[78:81], v[64:65], off
	v_lshlrev_b32_e32 v64, 7, v128
	v_ashrrev_i32_e32 v65, 31, v64
	v_lshl_add_u64 v[64:65], v[64:65], 1, v[112:113]
	global_load_dwordx4 v[112:115], v[64:65], off
	v_add_f32_e32 v64, v129, v90
	v_add_f32_e32 v64, v126, v64
	v_pk_mul_f32 v[124:125], v[56:57], v[56:57]
	v_add_f32_e32 v64, v127, v64
	v_add_f32_e32 v64, v124, v64
	v_pk_mul_f32 v[122:123], v[54:55], v[54:55]
	v_add_f32_e32 v64, v125, v64
	v_add_f32_e32 v64, v122, v64
	v_pk_mul_f32 v[120:121], v[52:53], v[52:53]
	v_add_f32_e32 v64, v123, v64
	v_add_f32_e32 v64, v120, v64
	v_pk_mul_f32 v[118:119], v[50:51], v[50:51]
	v_add_f32_e32 v64, v121, v64
	v_add_f32_e32 v64, v118, v64
	v_pk_mul_f32 v[116:117], v[48:49], v[48:49]
	v_add_f32_e32 v64, v119, v64
	v_add_f32_e32 v64, v116, v64
	v_pk_mul_f32 v[104:105], v[46:47], v[46:47]
	v_add_f32_e32 v64, v117, v64
	v_add_f32_e32 v64, v104, v64
	v_pk_mul_f32 v[96:97], v[44:45], v[44:45]
	v_add_f32_e32 v64, v105, v64
	v_add_f32_e32 v64, v96, v64
	v_pk_mul_f32 v[94:95], v[42:43], v[42:43]
	v_add_f32_e32 v64, v97, v64
	v_add_f32_e32 v64, v94, v64
	v_pk_mul_f32 v[92:93], v[40:41], v[40:41]
	v_add_f32_e32 v64, v95, v64
	v_add_f32_e32 v64, v92, v64
	v_pk_mul_f32 v[82:83], v[38:39], v[38:39]
	v_add_f32_e32 v64, v93, v64
	v_add_f32_e32 v64, v82, v64
	v_pk_mul_f32 v[68:69], v[36:37], v[36:37]
	v_add_f32_e32 v64, v83, v64
	v_add_f32_e32 v64, v68, v64
	v_pk_mul_f32 v[66:67], v[34:35], v[34:35]
	v_add_f32_e32 v64, v69, v64
	v_add_f32_e32 v64, v66, v64
	v_add_f32_e32 v64, v67, v64
	v_mov_b32_e32 v65, v64
	v_mul_lo_u32 v94, v106, s4
	v_and_b32_e32 v90, 31, v84
	s_waitcnt lgkmcnt(0)
	s_nop 1
	v_permlane32_swap_b32_e32 v64, v65
	v_add_f32_e32 v64, v64, v65
	v_fmamk_f32 v64, v64, 0x3c800000, v198
	v_mul_f32_e32 v65, 0x4b800000, v64
	v_cmp_gt_f32_e32 vcc, s92, v64
	s_waitcnt vmcnt(5)
	v_lshlrev_b32_e32 v93, 16, v87
	v_cndmask_b32_e32 v64, v64, v65, vcc
	v_rsq_f32_e32 v64, v64
	s_nop 0
	v_mul_f32_e32 v65, 0x45800000, v64
	v_cndmask_b32_e32 v64, v64, v65, vcc
	v_mul_f32_e32 v82, 0x3e38aa3b, v64
	v_pk_mul_f32 v[60:61], v[82:83], v[60:61] op_sel_hi:[0,1]
	v_pk_mul_f32 v[12:13], v[12:13], v[60:61]
	v_pk_mul_f32 v[58:59], v[82:83], v[58:59] op_sel_hi:[0,1]
	v_cvt_pk_bf16_f32 v66, v12, v13
	v_pk_mul_f32 v[12:13], v[82:83], v[56:57] op_sel_hi:[0,1]
	v_pk_mul_f32 v[8:9], v[8:9], v[12:13]
	v_pk_mul_f32 v[12:13], v[82:83], v[54:55] op_sel_hi:[0,1]
	v_pk_mul_f32 v[10:11], v[10:11], v[12:13]
	v_pk_mul_f32 v[12:13], v[82:83], v[52:53] op_sel_hi:[0,1]
	v_pk_mul_f32 v[14:15], v[14:15], v[58:59]
	v_pk_mul_f32 v[12:13], v[4:5], v[12:13]
	v_pk_mul_f32 v[4:5], v[82:83], v[50:51] op_sel_hi:[0,1]
	v_cvt_pk_bf16_f32 v67, v14, v15
	v_pk_mul_f32 v[14:15], v[6:7], v[4:5]
	v_add_u32_e32 v4, 32, v168
	v_add_u32_e32 v6, 32, v132
	v_cvt_pk_bf16_f32 v68, v8, v9
	v_add_u32_e32 v103, v4, v94
	v_mad_u64_u32 v[8:9], s[2:3], v33, s5, v[6:7]
	v_mad_u64_u32 v[4:5], s[2:3], v111, s4, v[4:5]
	v_add_u32_e32 v111, 32, v32
	s_waitcnt vmcnt(3)
	ds_write_b128 v103, v[70:73]
	s_waitcnt vmcnt(2)
	ds_write_b128 v8, v[74:77] offset:18432
	s_waitcnt vmcnt(1)
	ds_write_b128 v4, v[78:81]
	v_mad_u64_u32 v[4:5], s[2:3], v128, s5, v[6:7]
	v_mad_u32_u24 v92, v90, s4, v111
	s_waitcnt vmcnt(0)
	ds_write_b128 v4, v[112:115] offset:18432
	s_waitcnt lgkmcnt(0)
	s_barrier
	ds_read_b128 v[4:7], v92
	v_pk_mul_f32 v[64:65], v[82:83], v[130:131] op_sel_hi:[0,1]
	v_pk_mul_f32 v[62:63], v[82:83], v[62:63] op_sel_hi:[0,1]
	v_pk_mul_f32 v[28:29], v[28:29], v[64:65]
	v_pk_mul_f32 v[30:31], v[30:31], v[62:63]
	v_pk_mul_f32 v[8:9], v[82:83], v[48:49] op_sel_hi:[0,1]
	v_cvt_pk_bf16_f32 v64, v28, v29
	v_cvt_pk_bf16_f32 v65, v30, v31
	v_pk_mul_f32 v[32:33], v[0:1], v[8:9]
	v_pk_mul_f32 v[0:1], v[82:83], v[46:47] op_sel_hi:[0,1]
	ds_read_b128 v[28:31], v92 offset:32
	v_cvt_pk_bf16_f32 v69, v10, v11
	v_cvt_pk_bf16_f32 v70, v12, v13
	v_cvt_pk_bf16_f32 v71, v14, v15
	v_pk_mul_f32 v[46:47], v[2:3], v[0:1]
	s_waitcnt lgkmcnt(1)
	v_mfma_f32_32x32x16_bf16 v[0:15], v[4:7], v[64:67], 0
	v_mul_f32_e64 v44, v82, v44
	v_mul_f32_e64 v45, v82, v45
	v_mul_f32_e64 v24, v24, v44
	v_mul_f32_e64 v25, v25, v45
	v_mul_f32_e64 v42, v82, v42
	v_mul_f32_e64 v43, v82, v43
	v_pk_mul_f32 v[42:43], v[26:27], v[42:43]
	v_cvt_pk_bf16_f32 v74, v24, v25
	ds_read_b128 v[24:27], v92 offset:64
	v_cvt_pk_bf16_f32 v72, v32, v33
	s_waitcnt lgkmcnt(1)
	v_mfma_f32_32x32x16_bf16 v[0:15], v[28:31], v[68:71], v[0:15]
	v_mul_f32_e64 v28, v82, v40
	v_mul_f32_e64 v29, v82, v41
	v_mul_f32_e64 v28, v20, v28
	v_mul_f32_e64 v29, v21, v29
	v_mul_f32_e64 v20, v82, v38
	v_mul_f32_e64 v21, v82, v39
	v_cvt_pk_bf16_f32 v73, v46, v47
	v_cvt_pk_bf16_f32 v75, v42, v43
	v_pk_mul_f32 v[30:31], v[22:23], v[20:21]
	ds_read_b128 v[20:23], v92 offset:96
	s_waitcnt lgkmcnt(1)
	v_mfma_f32_32x32x16_bf16 v[0:15], v[24:27], v[72:75], v[0:15]
	v_mul_f32_e64 v32, v82, v36
	v_mul_f32_e64 v33, v82, v37
	v_mul_f32_e64 v24, v82, v34
	v_mul_f32_e64 v25, v82, v35
	v_mul_f32_e64 v16, v16, v32
	v_mul_f32_e64 v17, v17, v33
	v_pk_mul_f32 v[18:19], v[18:19], v[24:25]
	v_cvt_pk_bf16_f32 v78, v16, v17
	v_cvt_pk_bf16_f32 v79, v18, v19
	ds_read_b128 v[16:19], v92 offset:4608
	ds_read_b128 v[32:35], v92 offset:4640
	v_cvt_pk_bf16_f32 v76, v28, v29
	v_cvt_pk_bf16_f32 v77, v30, v31
	s_waitcnt lgkmcnt(2)
	s_nop 0
	v_mfma_f32_32x32x16_bf16 v[0:15], v[20:23], v[76:79], v[0:15]
	s_waitcnt lgkmcnt(1)
	v_mfma_f32_32x32x16_bf16 v[16:31], v[16:19], v[64:67], 0
	s_waitcnt lgkmcnt(0)
; DI float bf2f(bf16_t b) { return __uint_as_float(((unsigned)b) << 16); }
; DI float sigmf(float x) { return 1.f / (1.f + __expf(-x)); }
; DI int crow(int reg, int h) { return (reg & 3) + 8 * (reg >> 2) + 4 * h; }
; #define MFMA32(a, b, c) __builtin_amdgcn_mfma_f32_32x32x16_bf16((a), (b), (c), 0, 0, 0)
; DI void nsa_item(unsigned char* ws_, const float* qg, const bf16_t* proj, bf16_t* mix, int item, LP unsigned char* lds3) {
;     ...
;   const float g0 = sigmf(bf2f(proj[tokrow + N_GT + (g * 4 + hd) * 3 + 0]));
;   const float g1 = sigmf(bf2f(proj[tokrow + N_GT + (g * 4 + hd) * 3 + 1]));
;   const float g2 = sigmf(bf2f(proj[tokrow + N_GT + (g * 4 + hd) * 3 + 2]));
;   __syncthreads();
;   { const bf16_t* kc = (const bf16_t*)(p.ws + WS_KCMP) + (size_t)bg * 128 * 64; const bf16_t* vc = (const bf16_t*)(p.ws + WS_VCMP) + (size_t)bg * 64 * 128;
; #pragma unroll
;     for (int i = 0; i < 2; ++i) { const int idx = tid + 512 * i; { const int n = idx >> 3, c = idx & 7; *(u32x4*)(Ks + n * 72 + c * 8) = *(const u32x4*)(kc + n * 64 + c * 8); }
;       { const int dd = idx >> 4, c = idx & 15; *(u32x4*)(VTs + dd * 136 + c * 8) = *(const u32x4*)(vc + dd * 128 + c * 8); } } }
;   __syncthreads();
;   {
;     f32x16 x[4]; float mx = NEGF;
; #pragma unroll
;     for (int sub = 0; sub < 4; ++sub) { x[sub] = zero16();
; #pragma unroll
;       for (int kk = 0; kk < 4; ++kk) x[sub] = MFMA32(*(const bf16x8*)(Ks + (sub * 32 + r) * 72 + kk * 16 + 8 * hh), qf[kk], x[sub]);
; #pragma unroll
;       for (int i = 0; i < 16; ++i) { const int n = sub * 32 + crow(i, hh); const bool ok = (n < 127) && (16 * n + 31 <= t);
;         x[sub][i] = ok ? x[sub][i] : NEGF; mx = fmaxf(mx, x[sub][i]); } }
	v_mfma_f32_32x32x16_bf16 v[16:31], v[32:35], v[68:71], v[16:31]
	ds_read_b128 v[32:35], v92 offset:4672
	ds_read_b128 v[36:39], v92 offset:4704
	s_waitcnt lgkmcnt(1)
	v_mfma_f32_32x32x16_bf16 v[16:31], v[32:35], v[72:75], v[16:31]
	ds_read_b128 v[32:35], v92 offset:9216
	ds_read_b128 v[48:51], v92 offset:9248
	s_waitcnt lgkmcnt(2)
	v_mfma_f32_32x32x16_bf16 v[16:31], v[36:39], v[76:79], v[16:31]
	s_waitcnt lgkmcnt(1)
	v_mfma_f32_32x32x16_bf16 v[32:47], v[32:35], v[64:67], 0
	s_waitcnt lgkmcnt(0)
	v_mfma_f32_32x32x16_bf16 v[32:47], v[48:51], v[68:71], v[32:47]
	ds_read_b128 v[48:51], v92 offset:9280
	ds_read_b128 v[52:55], v92 offset:9312
	s_waitcnt lgkmcnt(1)
	v_mfma_f32_32x32x16_bf16 v[32:47], v[48:51], v[72:75], v[32:47]
	ds_read_b128 v[48:51], v92 offset:13824
	ds_read_b128 v[80:83], v92 offset:13856
	ds_read_b128 v[112:115], v92 offset:13920
	s_waitcnt lgkmcnt(3)
	v_mfma_f32_32x32x16_bf16 v[32:47], v[52:55], v[76:79], v[32:47]
	s_waitcnt lgkmcnt(2)
	v_mfma_f32_32x32x16_bf16 v[48:63], v[48:51], v[64:67], 0
	s_waitcnt lgkmcnt(1)
	v_mfma_f32_32x32x16_bf16 v[48:63], v[80:83], v[68:71], v[48:63]
	ds_read_b128 v[80:83], v92 offset:13888
	s_waitcnt lgkmcnt(0)
	v_mfma_f32_32x32x16_bf16 v[48:63], v[80:83], v[72:75], v[48:63]
	v_lshlrev_b32_e32 v83, 6, v89
	v_mul_f32_e32 v80, 0xbfb8aa3b, v93
	v_subrev_u32_e32 v82, 31, v101
	v_or_b32_e32 v93, 16, v83
	v_cmp_le_i32_e32 vcc, v93, v82
	v_or_b32_e32 v95, 0x7a0, v83
	v_or_b32_e32 v96, 0x780, v83
	v_mfma_f32_32x32x16_bf16 v[48:63], v[112:115], v[76:79], v[48:63]
	v_cndmask_b32_e32 v1, v201, v1, vcc
	v_cmp_le_i32_e32 vcc, v83, v82
	v_exp_f32_e32 v80, v80
	s_nop 0
	v_cndmask_b32_e32 v0, v201, v0, vcc
	v_cmp_le_i32_e32 vcc, v95, v82
	v_or_b32_e32 v95, 0x7b0, v83
	v_add_f32_e32 v92, 1.0, v80
	s_nop 3
	v_cndmask_b32_e32 v62, v201, v62, vcc
	v_cmp_le_i32_e32 vcc, v95, v82
	s_and_b64 vcc, s[6:7], vcc
	v_or_b32_e32 v95, 0x790, v83
	v_cndmask_b32_e32 v63, v201, v63, vcc
	v_cmp_le_i32_e32 vcc, v95, v82
	v_or_b32_e32 v95, 0x730, v83
	v_div_scale_f32 v81, s[2:3], v92, v92, 1.0
	v_cndmask_b32_e32 v61, v201, v61, vcc
	v_cmp_le_i32_e32 vcc, v96, v82
	v_or_b32_e32 v96, 0x720, v83
	s_mov_b32 s2, 0xf149f2ca
	v_cndmask_b32_e32 v60, v201, v60, vcc
	v_cmp_le_i32_e32 vcc, v95, v82
	v_or_b32_e32 v95, 0x710, v83
	v_max3_f32 v93, v0, s2, v1
	v_cndmask_b32_e32 v59, v201, v59, vcc
	v_cmp_le_i32_e32 vcc, v96, v82
	v_or_b32_e32 v96, 0x700, v83
	v_rcp_f32_e32 v80, v81
	v_cndmask_b32_e32 v58, v201, v58, vcc
	v_cmp_le_i32_e32 vcc, v95, v82
	v_or_b32_e32 v95, 0x6b0, v83
	s_mov_b32 s2, 0xefa18f08
	v_cndmask_b32_e32 v57, v201, v57, vcc
	v_cmp_le_i32_e32 vcc, v96, v82
	v_or_b32_e32 v96, 0x6a0, v83
	s_nop 0
	v_cndmask_b32_e32 v56, v201, v56, vcc
	v_cmp_le_i32_e32 vcc, v95, v82
	v_or_b32_e32 v95, 0x690, v83
	s_nop 0
	v_cndmask_b32_e32 v55, v201, v55, vcc
	v_cmp_le_i32_e32 vcc, v96, v82
	v_or_b32_e32 v96, 0x680, v83
	s_nop 0
	v_cndmask_b32_e32 v54, v201, v54, vcc
	v_cmp_le_i32_e32 vcc, v95, v82
	v_or_b32_e32 v95, 0x630, v83
	s_nop 0
	v_cndmask_b32_e32 v53, v201, v53, vcc
	v_cmp_le_i32_e32 vcc, v96, v82
	v_or_b32_e32 v96, 0x620, v83
	s_nop 0
	v_cndmask_b32_e32 v52, v201, v52, vcc
	v_cmp_le_i32_e32 vcc, v95, v82
	v_or_b32_e32 v95, 0x610, v83
	s_nop 0
	v_cndmask_b32_e32 v51, v201, v51, vcc
	v_cmp_le_i32_e32 vcc, v96, v82
	v_or_b32_e32 v96, 0x600, v83
	s_nop 0
	v_cndmask_b32_e32 v50, v201, v50, vcc
	v_cmp_le_i32_e32 vcc, v95, v82
	v_or_b32_e32 v95, 0x5b0, v83
	s_nop 0
	v_cndmask_b32_e32 v49, v201, v49, vcc
	v_cmp_le_i32_e32 vcc, v96, v82
	v_or_b32_e32 v96, 0x5a0, v83
	s_nop 0
	v_cndmask_b32_e32 v48, v201, v48, vcc
	v_cmp_le_i32_e32 vcc, v95, v82
	v_or_b32_e32 v95, 0x590, v83
	s_nop 0
	v_cndmask_b32_e32 v47, v201, v47, vcc
	v_cmp_le_i32_e32 vcc, v96, v82
	v_or_b32_e32 v96, 0x580, v83
	s_nop 0
	v_cndmask_b32_e32 v46, v201, v46, vcc
	v_cmp_le_i32_e32 vcc, v95, v82
	v_or_b32_e32 v95, 0x530, v83
	s_nop 0
	v_cndmask_b32_e32 v45, v201, v45, vcc
	v_cmp_le_i32_e32 vcc, v96, v82
	v_or_b32_e32 v96, 0x520, v83
	s_nop 0
	v_cndmask_b32_e32 v44, v201, v44, vcc
	v_cmp_le_i32_e32 vcc, v95, v82
	s_nop 1
	v_cndmask_b32_e32 v95, v201, v43, vcc
	v_cmp_le_i32_e32 vcc, v96, v82
	v_or_b32_e32 v43, 0x500, v83
	s_nop 0
	v_cndmask_b32_e32 v96, v201, v42, vcc
	v_or_b32_e32 v42, 0x510, v83
	v_cmp_le_i32_e32 vcc, v42, v82
	s_nop 1
	v_cndmask_b32_e32 v42, v201, v41, vcc
	v_cmp_le_i32_e32 vcc, v43, v82
	v_or_b32_e32 v41, 0x4a0, v83
	s_nop 0
	v_cndmask_b32_e32 v97, v201, v40, vcc
	v_or_b32_e32 v40, 0x4b0, v83
	v_cmp_le_i32_e32 vcc, v40, v82
	s_nop 1
	v_cndmask_b32_e32 v40, v201, v39, vcc
	v_cmp_le_i32_e32 vcc, v41, v82
	v_or_b32_e32 v39, 0x480, v83
	s_nop 0
	v_cndmask_b32_e32 v43, v201, v38, vcc
	v_or_b32_e32 v38, 0x490, v83
	v_cmp_le_i32_e32 vcc, v38, v82
	s_nop 1
	v_cndmask_b32_e32 v38, v201, v37, vcc
	v_cmp_le_i32_e32 vcc, v39, v82
	v_or_b32_e32 v37, 0x420, v83
	s_nop 0
	v_cndmask_b32_e32 v41, v201, v36, vcc
	v_or_b32_e32 v36, 0x430, v83
	v_cmp_le_i32_e32 vcc, v36, v82
	s_nop 1
	v_cndmask_b32_e32 v36, v201, v35, vcc
	v_cmp_le_i32_e32 vcc, v37, v82
	v_or_b32_e32 v35, 0x400, v83
	v_fma_f32 v37, -v81, v80, 1.0
	v_cndmask_b32_e32 v39, v201, v34, vcc
	v_or_b32_e32 v34, 0x410, v83
	v_cmp_le_i32_e32 vcc, v34, v82
	v_or_b32_e32 v34, 0x3b0, v83
	v_fmac_f32_e32 v80, v37, v80
	v_cndmask_b32_e32 v33, v201, v33, vcc
	v_cmp_le_i32_e32 vcc, v35, v82
	v_or_b32_e32 v35, 0x3a0, v83
	s_nop 0
	v_cndmask_b32_e32 v32, v201, v32, vcc
	v_cmp_le_i32_e32 vcc, v34, v82
	v_or_b32_e32 v34, 0x390, v83
	s_nop 0
	v_cndmask_b32_e32 v31, v201, v31, vcc
	v_cmp_le_i32_e32 vcc, v35, v82
	v_or_b32_e32 v35, 0x380, v83
	s_nop 0
	v_cndmask_b32_e32 v30, v201, v30, vcc
	v_cmp_le_i32_e32 vcc, v34, v82
; DI int crow(int reg, int h) { return (reg & 3) + 8 * (reg >> 2) + 4 * h; }
; DI void nsa_item(unsigned char* ws_, const float* qg, const bf16_t* proj, bf16_t* mix, int item, LP unsigned char* lds3) {
;     ...
;       for (int i = 0; i < 16; ++i) { const int n = sub * 32 + crow(i, hh); const bool ok = (n < 127) && (16 * n + 31 <= t);
;         x[sub][i] = ok ? x[sub][i] : NEGF; mx = fmaxf(mx, x[sub][i]); } }
;     mx = fmaxf(mx, __shfl_xor(mx, 32));
;     float ps = 0.f;
; #pragma unroll
;     for (int sub = 0; sub < 4; ++sub)
; #pragma unroll
;       for (int i = 0; i < 16; ++i) { const float pv = (x[sub][i] > -1e29f) ? __builtin_amdgcn_exp2f(x[sub][i] - mx) : 0.f; x[sub][i] = pv; ps += pv; }
	v_or_b32_e32 v34, 0x330, v83
	s_nop 0
	v_cndmask_b32_e32 v29, v201, v29, vcc
	v_cmp_le_i32_e32 vcc, v35, v82
	v_or_b32_e32 v35, 0x320, v83
	s_nop 0
	v_cndmask_b32_e32 v28, v201, v28, vcc
	v_cmp_le_i32_e32 vcc, v34, v82
	v_or_b32_e32 v34, 0x310, v83
	s_nop 0
	v_cndmask_b32_e32 v27, v201, v27, vcc
	v_cmp_le_i32_e32 vcc, v35, v82
	v_or_b32_e32 v35, 0x300, v83
	s_nop 0
	v_cndmask_b32_e32 v26, v201, v26, vcc
	v_cmp_le_i32_e32 vcc, v34, v82
	v_or_b32_e32 v34, 0x2b0, v83
	s_nop 0
	v_cndmask_b32_e32 v25, v201, v25, vcc
	v_cmp_le_i32_e32 vcc, v35, v82
	v_or_b32_e32 v35, 0x2a0, v83
	s_nop 0
	v_cndmask_b32_e32 v24, v201, v24, vcc
	v_cmp_le_i32_e32 vcc, v34, v82
	v_or_b32_e32 v34, 0x290, v83
	s_nop 0
	v_cndmask_b32_e32 v23, v201, v23, vcc
	v_cmp_le_i32_e32 vcc, v35, v82
	v_or_b32_e32 v35, 0x280, v83
	s_nop 0
	v_cndmask_b32_e32 v22, v201, v22, vcc
	v_cmp_le_i32_e32 vcc, v34, v82
	v_or_b32_e32 v34, 0x230, v83
	s_nop 0
	v_cndmask_b32_e32 v21, v201, v21, vcc
	v_cmp_le_i32_e32 vcc, v35, v82
	v_or_b32_e32 v35, 0x220, v83
	s_nop 0
	v_cndmask_b32_e32 v20, v201, v20, vcc
	v_cmp_le_i32_e32 vcc, v34, v82
	v_or_b32_e32 v34, 0x210, v83
	s_nop 0
	v_cndmask_b32_e32 v19, v201, v19, vcc
	v_cmp_le_i32_e32 vcc, v35, v82
	v_or_b32_e32 v35, 0x200, v83
	s_nop 0
	v_cndmask_b32_e32 v18, v201, v18, vcc
	v_cmp_le_i32_e32 vcc, v34, v82
	v_or_b32_e32 v34, 0x1b0, v83
	s_nop 0
	v_cndmask_b32_e32 v17, v201, v17, vcc
	v_cmp_le_i32_e32 vcc, v35, v82
	v_or_b32_e32 v35, 0x1a0, v83
	s_nop 0
	v_cndmask_b32_e32 v16, v201, v16, vcc
	v_cmp_le_i32_e32 vcc, v34, v82
	v_or_b32_e32 v34, 0x190, v83
	s_nop 0
	v_cndmask_b32_e32 v15, v201, v15, vcc
	v_cmp_le_i32_e32 vcc, v35, v82
	v_or_b32_e32 v35, 0x180, v83
	s_nop 0
	v_cndmask_b32_e32 v14, v201, v14, vcc
	v_cmp_le_i32_e32 vcc, v34, v82
	v_or_b32_e32 v34, 0x130, v83
	s_nop 0
	v_cndmask_b32_e32 v13, v201, v13, vcc
	v_cmp_le_i32_e32 vcc, v35, v82
	v_or_b32_e32 v35, 0x120, v83
	s_nop 0
	v_cndmask_b32_e32 v12, v201, v12, vcc
	v_cmp_le_i32_e32 vcc, v34, v82
	v_or_b32_e32 v34, 0x110, v83
	s_nop 0
	v_cndmask_b32_e32 v11, v201, v11, vcc
	v_cmp_le_i32_e32 vcc, v35, v82
	v_or_b32_e32 v35, 0x100, v83
	s_nop 0
	v_cndmask_b32_e32 v10, v201, v10, vcc
	v_cmp_le_i32_e32 vcc, v34, v82
	v_or_b32_e32 v34, 0xb0, v83
	s_nop 0
	v_cndmask_b32_e32 v9, v201, v9, vcc
	v_cmp_le_i32_e32 vcc, v35, v82
	v_or_b32_e32 v35, 0xa0, v83
	s_nop 0
	v_cndmask_b32_e32 v8, v201, v8, vcc
	v_cmp_le_i32_e32 vcc, v34, v82
	v_or_b32_e32 v34, 0x90, v83
	s_nop 0
	v_cndmask_b32_e32 v7, v201, v7, vcc
	v_cmp_le_i32_e32 vcc, v35, v82
	v_or_b32_e32 v35, 0x80, v83
	s_nop 0
	v_cndmask_b32_e32 v6, v201, v6, vcc
	v_cmp_le_i32_e32 vcc, v34, v82
	v_or_b32_e32 v34, 48, v83
	s_nop 0
	v_cndmask_b32_e32 v5, v201, v5, vcc
	v_cmp_le_i32_e32 vcc, v35, v82
	v_or_b32_e32 v35, 32, v83
	s_nop 0
	v_cndmask_b32_e32 v4, v201, v4, vcc
	v_cmp_le_i32_e32 vcc, v34, v82
	s_nop 1
	v_cndmask_b32_e32 v3, v201, v3, vcc
	v_cmp_le_i32_e32 vcc, v35, v82
	s_nop 1
	v_cndmask_b32_e32 v2, v201, v2, vcc
	v_max3_f32 v34, v93, v2, v3
	v_max3_f32 v34, v34, v4, v5
	v_max3_f32 v34, v34, v6, v7
	v_max3_f32 v34, v34, v8, v9
	v_max3_f32 v34, v34, v10, v11
	v_max3_f32 v34, v34, v12, v13
	v_max3_f32 v34, v34, v14, v15
	v_max3_f32 v34, v34, v16, v17
	v_max3_f32 v34, v34, v18, v19
	v_max3_f32 v34, v34, v20, v21
	v_max3_f32 v34, v34, v22, v23
	v_max3_f32 v34, v34, v24, v25
	v_max3_f32 v34, v34, v26, v27
	v_max3_f32 v34, v34, v28, v29
	v_max3_f32 v34, v34, v30, v31
	v_max3_f32 v34, v34, v32, v33
	v_max3_f32 v34, v34, v39, v36
	v_max3_f32 v34, v34, v41, v38
	v_max3_f32 v34, v34, v43, v40
	v_max3_f32 v34, v34, v97, v42
	v_max3_f32 v34, v34, v96, v95
	v_max3_f32 v34, v34, v44, v45
	v_max3_f32 v34, v34, v46, v47
	v_max3_f32 v34, v34, v48, v49
	v_max3_f32 v34, v34, v50, v51
	v_max3_f32 v34, v34, v52, v53
	v_max3_f32 v34, v34, v54, v55
	v_max3_f32 v34, v34, v56, v57
	v_max3_f32 v34, v34, v58, v59
	v_max3_f32 v34, v34, v60, v61
	v_max3_f32 v34, v34, v62, v63
	ds_bpermute_b32 v35, v102, v34
	v_cmp_lt_f32_e32 vcc, s2, v1
	s_waitcnt lgkmcnt(0)
	v_max_f32_e32 v35, v35, v35
	v_max_f32_e32 v82, v34, v35
	v_sub_f32_e32 v34, v1, v82
	v_exp_f32_e32 v34, v34
	v_sub_f32_e32 v35, v0, v82
	v_exp_f32_e32 v35, v35
	v_sub_f32_e32 v37, v2, v82
	v_cndmask_b32_e32 v1, 0, v34, vcc
	v_cmp_lt_f32_e32 vcc, s2, v0
	v_exp_f32_e32 v37, v37
	s_nop 0
	v_cndmask_b32_e32 v0, 0, v35, vcc
	v_sub_f32_e32 v35, v3, v82
	v_exp_f32_e32 v35, v35
	v_cmp_lt_f32_e32 vcc, s2, v3
	v_add_f32_e32 v34, 0, v0
	v_add_f32_e32 v34, v1, v34
	v_cndmask_b32_e32 v3, 0, v35, vcc
	v_cmp_lt_f32_e32 vcc, s2, v2
	v_sub_f32_e32 v35, v5, v82
	v_exp_f32_e32 v35, v35
	v_cndmask_b32_e32 v2, 0, v37, vcc
	v_sub_f32_e32 v37, v4, v82
	v_exp_f32_e32 v37, v37
	v_cmp_lt_f32_e32 vcc, s2, v5
	v_add_f32_e32 v34, v2, v34
	v_add_f32_e32 v34, v3, v34
	v_cndmask_b32_e32 v5, 0, v35, vcc
	v_cmp_lt_f32_e32 vcc, s2, v4
	v_sub_f32_e32 v35, v7, v82
	v_exp_f32_e32 v35, v35
	v_cndmask_b32_e32 v4, 0, v37, vcc
	v_sub_f32_e32 v37, v6, v82
	v_exp_f32_e32 v37, v37
	v_cmp_lt_f32_e32 vcc, s2, v7
	v_add_f32_e32 v34, v4, v34
	v_add_f32_e32 v34, v5, v34
	v_cndmask_b32_e32 v7, 0, v35, vcc
	v_cmp_lt_f32_e32 vcc, s2, v6
	v_sub_f32_e32 v35, v9, v82
	v_exp_f32_e32 v35, v35
	v_cndmask_b32_e32 v6, 0, v37, vcc
	v_sub_f32_e32 v37, v8, v82
	v_exp_f32_e32 v37, v37
	v_cmp_lt_f32_e32 vcc, s2, v9
	v_add_f32_e32 v34, v6, v34
	v_add_f32_e32 v34, v7, v34
	v_cndmask_b32_e32 v9, 0, v35, vcc
	v_cmp_lt_f32_e32 vcc, s2, v8
	v_sub_f32_e32 v35, v11, v82
	v_exp_f32_e32 v35, v35
	v_cndmask_b32_e32 v8, 0, v37, vcc
	v_sub_f32_e32 v37, v10, v82
	v_exp_f32_e32 v37, v37
	v_cmp_lt_f32_e32 vcc, s2, v11
	v_add_f32_e32 v34, v8, v34
	v_add_f32_e32 v34, v9, v34
	v_cndmask_b32_e32 v11, 0, v35, vcc
; DI void nsa_item(unsigned char* ws_, const float* qg, const bf16_t* proj, bf16_t* mix, int item, LP unsigned char* lds3) {
;     ...
;     float ps = 0.f;
; #pragma unroll
;     for (int sub = 0; sub < 4; ++sub)
; #pragma unroll
;       for (int i = 0; i < 16; ++i) { const float pv = (x[sub][i] > -1e29f) ? __builtin_amdgcn_exp2f(x[sub][i] - mx) : 0.f; x[sub][i] = pv; ps += pv; }
	v_cmp_lt_f32_e32 vcc, s2, v10
	v_sub_f32_e32 v35, v13, v82
	v_exp_f32_e32 v35, v35
	v_cndmask_b32_e32 v10, 0, v37, vcc
	v_sub_f32_e32 v37, v12, v82
	v_exp_f32_e32 v37, v37
	v_cmp_lt_f32_e32 vcc, s2, v13
	v_add_f32_e32 v34, v10, v34
	v_add_f32_e32 v34, v11, v34
	v_cndmask_b32_e32 v13, 0, v35, vcc
	v_cmp_lt_f32_e32 vcc, s2, v12
	v_sub_f32_e32 v35, v15, v82
	v_exp_f32_e32 v35, v35
	v_cndmask_b32_e32 v12, 0, v37, vcc
	v_sub_f32_e32 v37, v14, v82
	v_exp_f32_e32 v37, v37
	v_cmp_lt_f32_e32 vcc, s2, v15
	v_add_f32_e32 v34, v12, v34
	v_add_f32_e32 v34, v13, v34
	v_cndmask_b32_e32 v15, 0, v35, vcc
	v_cmp_lt_f32_e32 vcc, s2, v14
	v_sub_f32_e32 v35, v17, v82
	v_exp_f32_e32 v35, v35
	v_cndmask_b32_e32 v14, 0, v37, vcc
	v_sub_f32_e32 v37, v16, v82
	v_exp_f32_e32 v37, v37
	v_cmp_lt_f32_e32 vcc, s2, v17
	v_add_f32_e32 v34, v14, v34
	v_add_f32_e32 v34, v15, v34
	v_cndmask_b32_e32 v17, 0, v35, vcc
	v_cmp_lt_f32_e32 vcc, s2, v16
	v_sub_f32_e32 v35, v19, v82
	v_exp_f32_e32 v35, v35
	v_cndmask_b32_e32 v16, 0, v37, vcc
	v_sub_f32_e32 v37, v18, v82
	v_exp_f32_e32 v37, v37
	v_cmp_lt_f32_e32 vcc, s2, v19
	v_add_f32_e32 v34, v16, v34
	v_add_f32_e32 v34, v17, v34
	v_cndmask_b32_e32 v19, 0, v35, vcc
	v_cmp_lt_f32_e32 vcc, s2, v18
	v_sub_f32_e32 v35, v21, v82
	v_exp_f32_e32 v35, v35
	v_cndmask_b32_e32 v18, 0, v37, vcc
	v_sub_f32_e32 v37, v20, v82
	v_exp_f32_e32 v37, v37
	v_cmp_lt_f32_e32 vcc, s2, v21
	v_add_f32_e32 v34, v18, v34
	v_add_f32_e32 v34, v19, v34
	v_cndmask_b32_e32 v21, 0, v35, vcc
	v_cmp_lt_f32_e32 vcc, s2, v20
	v_sub_f32_e32 v35, v23, v82
	v_exp_f32_e32 v35, v35
	v_cndmask_b32_e32 v20, 0, v37, vcc
	v_sub_f32_e32 v37, v22, v82
	v_exp_f32_e32 v37, v37
	v_cmp_lt_f32_e32 vcc, s2, v23
	v_add_f32_e32 v34, v20, v34
	v_add_f32_e32 v34, v21, v34
	v_cndmask_b32_e32 v23, 0, v35, vcc
	v_cmp_lt_f32_e32 vcc, s2, v22
	v_sub_f32_e32 v35, v25, v82
	v_exp_f32_e32 v35, v35
	v_cndmask_b32_e32 v22, 0, v37, vcc
	v_sub_f32_e32 v37, v24, v82
	v_exp_f32_e32 v37, v37
	v_cmp_lt_f32_e32 vcc, s2, v25
	v_add_f32_e32 v34, v22, v34
	v_add_f32_e32 v34, v23, v34
	v_cndmask_b32_e32 v25, 0, v35, vcc
	v_cmp_lt_f32_e32 vcc, s2, v24
	v_sub_f32_e32 v35, v27, v82
	v_exp_f32_e32 v35, v35
	v_cndmask_b32_e32 v24, 0, v37, vcc
	v_sub_f32_e32 v37, v26, v82
	v_exp_f32_e32 v37, v37
	v_cmp_lt_f32_e32 vcc, s2, v27
	v_add_f32_e32 v34, v24, v34
	v_add_f32_e32 v34, v25, v34
	v_cndmask_b32_e32 v27, 0, v35, vcc
	v_cmp_lt_f32_e32 vcc, s2, v26
	v_sub_f32_e32 v35, v29, v82
	v_exp_f32_e32 v35, v35
	v_cndmask_b32_e32 v26, 0, v37, vcc
	v_sub_f32_e32 v37, v28, v82
	v_exp_f32_e32 v37, v37
	v_cmp_lt_f32_e32 vcc, s2, v29
	v_add_f32_e32 v34, v26, v34
	v_add_f32_e32 v34, v27, v34
	v_cndmask_b32_e32 v29, 0, v35, vcc
	v_cmp_lt_f32_e32 vcc, s2, v28
	v_sub_f32_e32 v35, v31, v82
	v_exp_f32_e32 v35, v35
	v_cndmask_b32_e32 v28, 0, v37, vcc
	v_sub_f32_e32 v37, v30, v82
	v_exp_f32_e32 v37, v37
	v_cmp_lt_f32_e32 vcc, s2, v31
	v_add_f32_e32 v34, v28, v34
	v_add_f32_e32 v34, v29, v34
	v_cndmask_b32_e32 v31, 0, v35, vcc
	v_cmp_lt_f32_e32 vcc, s2, v30
	v_sub_f32_e32 v35, v32, v82
	v_exp_f32_e32 v83, v35
	v_cndmask_b32_e32 v30, 0, v37, vcc
	v_add_f32_e32 v34, v30, v34
	v_add_f32_e32 v37, v31, v34
	v_sub_f32_e32 v34, v33, v82
	v_exp_f32_e32 v34, v34
	v_cmp_lt_f32_e32 vcc, s2, v33
	v_sub_f32_e32 v33, v36, v82
	v_exp_f32_e32 v33, v33
	v_cndmask_b32_e32 v35, 0, v34, vcc
	v_cmp_lt_f32_e32 vcc, s2, v32
	s_nop 1
	v_cndmask_b32_e32 v34, 0, v83, vcc
	v_add_f32_e32 v32, v34, v37
	v_sub_f32_e32 v37, v39, v82
	v_cmp_lt_f32_e32 vcc, s2, v36
	v_exp_f32_e32 v83, v37
	v_add_f32_e32 v32, v35, v32
	v_cndmask_b32_e32 v37, 0, v33, vcc
	v_sub_f32_e32 v33, v38, v82
	v_exp_f32_e32 v33, v33
	v_cmp_lt_f32_e32 vcc, s2, v39
	v_sub_f32_e32 v39, v41, v82
	s_nop 0
	v_cndmask_b32_e32 v36, 0, v83, vcc
	v_cmp_lt_f32_e32 vcc, s2, v38
	v_exp_f32_e32 v83, v39
	v_add_f32_e32 v32, v36, v32
	v_cndmask_b32_e32 v39, 0, v33, vcc
	v_sub_f32_e32 v33, v40, v82
	v_exp_f32_e32 v33, v33
	v_cmp_lt_f32_e32 vcc, s2, v41
	v_sub_f32_e32 v41, v43, v82
	v_add_f32_e32 v32, v37, v32
	v_cndmask_b32_e32 v38, 0, v83, vcc
	v_cmp_lt_f32_e32 vcc, s2, v40
	v_exp_f32_e32 v83, v41
	v_add_f32_e32 v32, v38, v32
	v_cndmask_b32_e32 v41, 0, v33, vcc
	v_sub_f32_e32 v33, v42, v82
	v_exp_f32_e32 v33, v33
	v_cmp_lt_f32_e32 vcc, s2, v43
	v_sub_f32_e32 v43, v97, v82
	v_add_f32_e32 v32, v39, v32
	v_cndmask_b32_e32 v40, 0, v83, vcc
	v_cmp_lt_f32_e32 vcc, s2, v42
	v_exp_f32_e32 v83, v43
	v_add_f32_e32 v32, v40, v32
	v_cndmask_b32_e32 v43, 0, v33, vcc
	v_sub_f32_e32 v33, v95, v82
	v_exp_f32_e32 v33, v33
	v_cmp_lt_f32_e32 vcc, s2, v97
	v_add_f32_e32 v32, v41, v32
	s_nop 0
	v_cndmask_b32_e32 v42, 0, v83, vcc
	v_sub_f32_e32 v83, v96, v82
	v_cmp_lt_f32_e32 vcc, s2, v95
	v_exp_f32_e32 v83, v83
	v_add_f32_e32 v32, v42, v32
	v_cndmask_b32_e32 v97, 0, v33, vcc
	v_sub_f32_e32 v33, v45, v82
	v_exp_f32_e32 v33, v33
	v_cmp_lt_f32_e32 vcc, s2, v96
	v_add_f32_e32 v32, v43, v32
	s_nop 0
	v_cndmask_b32_e32 v96, 0, v83, vcc
	v_sub_f32_e32 v83, v44, v82
	v_cmp_lt_f32_e32 vcc, s2, v45
	v_exp_f32_e32 v83, v83
	v_add_f32_e32 v32, v96, v32
	v_cndmask_b32_e32 v45, 0, v33, vcc
	v_sub_f32_e32 v33, v47, v82
	v_exp_f32_e32 v33, v33
	v_cmp_lt_f32_e32 vcc, s2, v44
	v_add_f32_e32 v32, v97, v32
	s_nop 0
	v_cndmask_b32_e32 v44, 0, v83, vcc
	v_sub_f32_e32 v83, v46, v82
	v_cmp_lt_f32_e32 vcc, s2, v47
	v_exp_f32_e32 v83, v83
	v_add_f32_e32 v32, v44, v32
	v_cndmask_b32_e32 v47, 0, v33, vcc
	v_sub_f32_e32 v33, v49, v82
	v_exp_f32_e32 v33, v33
	v_cmp_lt_f32_e32 vcc, s2, v46
	v_add_f32_e32 v32, v45, v32
	s_nop 0
	v_cndmask_b32_e32 v46, 0, v83, vcc
	v_sub_f32_e32 v83, v48, v82
	v_cmp_lt_f32_e32 vcc, s2, v49
	v_exp_f32_e32 v83, v83
	v_add_f32_e32 v32, v46, v32
; DI void nsa_item(unsigned char* ws_, const float* qg, const bf16_t* proj, bf16_t* mix, int item, LP unsigned char* lds3) {
;     ...
;       for (int i = 0; i < 16; ++i) { const float pv = (x[sub][i] > -1e29f) ? __builtin_amdgcn_exp2f(x[sub][i] - mx) : 0.f; x[sub][i] = pv; ps += pv; }
;     ps += __shfl_xor(ps, 32);
;     const float inv = ps > 0.f ? 1.f / ps : 0.f;
;     float Gs[16], last[16];
; #pragma unroll
;     for (int sub = 0; sub < 4; ++sub)
; #pragma unroll
;       for (int gq = 0; gq < 4; ++gq) {
; #pragma unroll
;         for (int e = 0; e < 4; ++e) x[sub][4 * gq + e] *= inv;
;         Gs[sub * 4 + gq] = (x[sub][4 * gq] + x[sub][4 * gq + 1]) + (x[sub][4 * gq + 2] + x[sub][4 * gq + 3]); last[sub * 4 + gq] = x[sub][4 * gq + 3]; }
; #pragma unroll
;     for (int mi = 0; mi < 16; ++mi) { const float rc = __shfl_xor(last[mi], 32); const float rp = (mi > 0) ? __shfl_xor(last[mi > 0 ? mi - 1 : 0], 32) : 0.f;
;       imp[(hd * 64 + tl) * 32 + 2 * mi + hh] = Gs[mi] + (hh ? rc : rp); }
	v_cndmask_b32_e32 v105, 0, v33, vcc
	v_sub_f32_e32 v33, v51, v82
	v_cmp_lt_f32_e32 vcc, s2, v48
	v_exp_f32_e32 v33, v33
	v_sub_f32_e32 v48, v50, v82
	v_exp_f32_e32 v48, v48
	v_cndmask_b32_e32 v104, 0, v83, vcc
	v_cmp_lt_f32_e32 vcc, s2, v51
	v_add_f32_e32 v32, v47, v32
	v_add_f32_e32 v32, v104, v32
	v_cndmask_b32_e32 v113, 0, v33, vcc
	v_cmp_lt_f32_e32 vcc, s2, v50
	v_sub_f32_e32 v33, v53, v82
	v_exp_f32_e32 v33, v33
	v_cndmask_b32_e32 v112, 0, v48, vcc
	v_sub_f32_e32 v48, v52, v82
	v_exp_f32_e32 v48, v48
	v_cmp_lt_f32_e32 vcc, s2, v53
	v_add_f32_e32 v32, v105, v32
	v_add_f32_e32 v32, v112, v32
	v_cndmask_b32_e32 v115, 0, v33, vcc
	v_cmp_lt_f32_e32 vcc, s2, v52
	v_sub_f32_e32 v33, v55, v82
	v_exp_f32_e32 v33, v33
	v_cndmask_b32_e32 v114, 0, v48, vcc
	v_sub_f32_e32 v48, v54, v82
	v_exp_f32_e32 v48, v48
	v_cmp_lt_f32_e32 vcc, s2, v55
	v_add_f32_e32 v32, v113, v32
	v_add_f32_e32 v32, v114, v32
	v_cndmask_b32_e32 v117, 0, v33, vcc
	v_cmp_lt_f32_e32 vcc, s2, v54
	v_sub_f32_e32 v33, v57, v82
	v_exp_f32_e32 v33, v33
	v_cndmask_b32_e32 v116, 0, v48, vcc
	v_sub_f32_e32 v48, v56, v82
	v_exp_f32_e32 v48, v48
	v_cmp_lt_f32_e32 vcc, s2, v57
	v_add_f32_e32 v32, v115, v32
	v_add_f32_e32 v32, v116, v32
	v_cndmask_b32_e32 v119, 0, v33, vcc
	v_cmp_lt_f32_e32 vcc, s2, v56
	v_sub_f32_e32 v33, v59, v82
	v_exp_f32_e32 v33, v33
	v_cndmask_b32_e32 v118, 0, v48, vcc
	v_sub_f32_e32 v48, v58, v82
	v_exp_f32_e32 v48, v48
	v_cmp_lt_f32_e32 vcc, s2, v59
	v_add_f32_e32 v32, v117, v32
	v_add_f32_e32 v32, v118, v32
	v_cndmask_b32_e32 v121, 0, v33, vcc
	v_cmp_lt_f32_e32 vcc, s2, v58
	v_sub_f32_e32 v33, v61, v82
	v_exp_f32_e32 v33, v33
	v_cndmask_b32_e32 v120, 0, v48, vcc
	v_sub_f32_e32 v48, v60, v82
	v_exp_f32_e32 v48, v48
	v_cmp_lt_f32_e32 vcc, s2, v61
	v_add_f32_e32 v32, v119, v32
	v_add_f32_e32 v32, v120, v32
	v_cndmask_b32_e32 v123, 0, v33, vcc
	v_cmp_lt_f32_e32 vcc, s2, v60
	v_sub_f32_e32 v33, v62, v82
	v_exp_f32_e32 v33, v33
	v_cndmask_b32_e32 v122, 0, v48, vcc
	v_sub_f32_e32 v48, v63, v82
	v_exp_f32_e32 v48, v48
	v_add_f32_e32 v32, v121, v32
	v_add_f32_e32 v32, v122, v32
	v_cmp_lt_f32_e32 vcc, s2, v62
	v_add_f32_e32 v32, v123, v32
	s_nop 0
	v_cndmask_b32_e32 v33, 0, v33, vcc
	v_cmp_lt_f32_e32 vcc, s2, v63
	v_add_f32_e32 v32, v33, v32
	s_nop 0
	v_cndmask_b32_e32 v93, 0, v48, vcc
	v_add_f32_e32 v32, v93, v32
	v_mov_b32_e32 v48, v32
	v_div_scale_f32 v49, vcc, 1.0, v92, 1.0
	v_mul_f32_e32 v50, v49, v80
	v_fma_f32 v51, -v81, v50, v49
	s_waitcnt lgkmcnt(0)
	s_nop 1
	v_permlane32_swap_b32_e32 v32, v48
	v_add_f32_e32 v32, v32, v48
	v_div_scale_f32 v48, s[2:3], v32, v32, 1.0
	v_fmac_f32_e32 v50, v51, v80
	v_rcp_f32_e32 v51, v48
	v_fma_f32 v49, -v81, v50, v49
	v_div_fmas_f32 v95, v49, v80, v50
	v_fma_f32 v49, -v48, v51, 1.0
	v_fmac_f32_e32 v51, v49, v51
	v_div_scale_f32 v49, vcc, 1.0, v32, 1.0
	v_mul_f32_e32 v50, v49, v51
	v_fma_f32 v52, -v48, v50, v49
	v_fmac_f32_e32 v50, v52, v51
	v_fma_f32 v48, -v48, v50, v49
	v_div_fmas_f32 v48, v48, v51, v50
	v_div_fixup_f32 v48, v48, v32, 1.0
	v_cmp_lt_f32_e32 vcc, 0, v32
	s_nop 1
	v_cndmask_b32_e32 v32, 0, v48, vcc
	v_pk_mul_f32 v[4:5], v[4:5], v[32:33] op_sel_hi:[1,0]
	v_pk_mul_f32 v[6:7], v[6:7], v[32:33] op_sel_hi:[1,0]
	v_pk_mul_f32 v[124:125], v[0:1], v[32:33] op_sel_hi:[1,0]
	v_add_f32_e32 v0, v6, v7
	v_add_f32_e32 v1, v4, v5
	v_pk_mul_f32 v[128:129], v[8:9], v[32:33] op_sel_hi:[1,0]
	v_pk_mul_f32 v[130:131], v[10:11], v[32:33] op_sel_hi:[1,0]
	v_pk_mul_f32 v[126:127], v[2:3], v[32:33] op_sel_hi:[1,0]
	v_add_f32_e32 v0, v1, v0
	v_add_f32_e32 v1, v130, v131
	v_add_f32_e32 v2, v128, v129
	v_pk_mul_f32 v[132:133], v[12:13], v[32:33] op_sel_hi:[1,0]
	v_pk_mul_f32 v[134:135], v[14:15], v[32:33] op_sel_hi:[1,0]
	v_add_f32_e32 v1, v2, v1
	v_add_f32_e32 v2, v134, v135
	v_add_f32_e32 v3, v132, v133
	v_pk_mul_f32 v[136:137], v[16:17], v[32:33] op_sel_hi:[1,0]
	v_pk_mul_f32 v[138:139], v[18:19], v[32:33] op_sel_hi:[1,0]
	v_add_f32_e32 v2, v3, v2
	v_add_f32_e32 v3, v138, v139
	v_add_f32_e32 v8, v136, v137
	v_pk_mul_f32 v[140:141], v[20:21], v[32:33] op_sel_hi:[1,0]
	v_pk_mul_f32 v[142:143], v[22:23], v[32:33] op_sel_hi:[1,0]
	v_add_f32_e32 v3, v8, v3
	v_add_f32_e32 v8, v142, v143
	v_add_f32_e32 v9, v140, v141
	v_pk_mul_f32 v[80:81], v[24:25], v[32:33] op_sel_hi:[1,0]
	v_pk_mul_f32 v[82:83], v[26:27], v[32:33] op_sel_hi:[1,0]
	v_add_f32_e32 v8, v9, v8
	v_add_f32_e32 v9, v82, v83
	v_add_f32_e32 v10, v80, v81
	v_pk_mul_f32 v[144:145], v[28:29], v[32:33] op_sel_hi:[1,0]
	v_pk_mul_f32 v[146:147], v[30:31], v[32:33] op_sel_hi:[1,0]
	v_add_f32_e32 v9, v10, v9
	v_add_f32_e32 v10, v146, v147
	v_add_f32_e32 v11, v144, v145
	v_pk_mul_f32 v[56:57], v[34:35], v[32:33] op_sel_hi:[1,0]
	v_pk_mul_f32 v[58:59], v[36:37], v[32:33] op_sel_hi:[1,0]
	v_add_f32_e32 v10, v11, v10
	v_add_f32_e32 v11, v58, v59
	v_add_f32_e32 v12, v56, v57
	v_pk_mul_f32 v[60:61], v[38:39], v[32:33] op_sel_hi:[1,0]
	v_pk_mul_f32 v[62:63], v[40:41], v[32:33] op_sel_hi:[1,0]
	v_add_f32_e32 v11, v12, v11
	v_add_f32_e32 v12, v62, v63
	v_add_f32_e32 v13, v60, v61
	v_pk_mul_f32 v[48:49], v[42:43], v[32:33] op_sel_hi:[1,0]
	v_pk_mul_f32 v[50:51], v[96:97], v[32:33] op_sel_hi:[1,0]
	v_add_f32_e32 v12, v13, v12
	v_add_f32_e32 v13, v50, v51
	v_add_f32_e32 v14, v48, v49
	v_pk_mul_f32 v[52:53], v[44:45], v[32:33] op_sel_hi:[1,0]
	v_pk_mul_f32 v[54:55], v[46:47], v[32:33] op_sel_hi:[1,0]
	v_add_f32_e32 v13, v14, v13
	v_add_f32_e32 v14, v54, v55
	v_add_f32_e32 v15, v52, v53
	v_pk_mul_f32 v[40:41], v[104:105], v[32:33] op_sel_hi:[1,0]
	v_pk_mul_f32 v[42:43], v[112:113], v[32:33] op_sel_hi:[1,0]
	v_add_f32_e32 v14, v15, v14
	v_add_f32_e32 v15, v42, v43
	v_add_f32_e32 v16, v40, v41
	v_pk_mul_f32 v[44:45], v[114:115], v[32:33] op_sel_hi:[1,0]
	v_pk_mul_f32 v[46:47], v[116:117], v[32:33] op_sel_hi:[1,0]
	v_add_f32_e32 v15, v16, v15
	v_add_f32_e32 v16, v46, v47
	v_add_f32_e32 v17, v44, v45
	v_pk_mul_f32 v[34:35], v[118:119], v[32:33] op_sel_hi:[1,0]
	v_pk_mul_f32 v[36:37], v[120:121], v[32:33] op_sel_hi:[1,0]
	v_add_f32_e32 v16, v17, v16
	v_add_f32_e32 v17, v36, v37
	v_add_f32_e32 v18, v34, v35
	v_pk_mul_f32 v[38:39], v[122:123], v[32:33] op_sel_hi:[1,0]
	v_mul_f32_e32 v93, v93, v32
	v_add_f32_e32 v17, v18, v17
	v_add_f32_e32 v18, v38, v39
	v_fma_f32 v19, v33, v32, v93
	v_add_f32_e32 v18, v18, v19
	v_lshl_add_u32 v19, v91, 13, 32
	v_lshlrev_b32_e32 v20, 7, v109
	v_lshlrev_b32_e32 v104, 2, v89
	v_add3_u32 v19, v19, v20, v104
	ds_bpermute_b32 v20, v102, v127
	ds_bpermute_b32 v22, v102, v7
	v_add_f32_e32 v21, v126, v127
	v_add_f32_e32 v23, v124, v125
	v_add_f32_e32 v21, v23, v21
	s_waitcnt lgkmcnt(1)
; #define MFMA32(a, b, c) __builtin_amdgcn_mfma_f32_32x32x16_bf16((a), (b), (c), 0, 0, 0)
; DI void nsa_item(unsigned char* ws_, const float* qg, const bf16_t* proj, bf16_t* mix, int item, LP unsigned char* lds3) {
;     ...
; #pragma unroll
;     for (int mi = 0; mi < 16; ++mi) { const float rc = __shfl_xor(last[mi], 32); const float rp = (mi > 0) ? __shfl_xor(last[mi > 0 ? mi - 1 : 0], 32) : 0.f;
;       imp[(hd * 64 + tl) * 32 + 2 * mi + hh] = Gs[mi] + (hh ? rc : rp); }
;     f32x16 comb[2]; comb[0] = zero16(); comb[1] = zero16();
; #pragma unroll
;     for (int sub = 0; sub < 4; ++sub)
; #pragma unroll
;       for (int s2 = 0; s2 < 2; ++s2) {
;         const bf16x8 pb = pack8(x[sub][8 * s2], x[sub][8 * s2 + 1], x[sub][8 * s2 + 2], x[sub][8 * s2 + 3], x[sub][8 * s2 + 4], x[sub][8 * s2 + 5], x[sub][8 * s2 + 6], x[sub][8 * s2 + 7]);
; #pragma unroll
;         for (int dt = 0; dt < 2; ++dt) { const bf16_t* vp = VTs + (dt * 32 + r) * 136 + sub * 32 + 16 * s2 + 4 * hh;
;           const s16x4 lo = *(const s16x4*)vp, hi = *(const s16x4*)(vp + 8);
;           const bf16x8 va = __builtin_shufflevector(lo, hi, 0, 1, 2, 3, 4, 5, 6, 7);
;           comb[dt] = MFMA32(va, pb, comb[dt]); } }
	v_cndmask_b32_e64 v23, v20, 0, s[6:7]
	v_add_f32_e32 v21, v23, v21
	s_waitcnt lgkmcnt(0)
	v_cndmask_b32_e64 v20, v22, v20, s[6:7]
	ds_bpermute_b32 v23, v102, v131
	v_add_f32_e32 v0, v0, v20
	ds_bpermute_b32 v20, v102, v135
	v_add_u32_e32 v19, 0x8c00, v19
	ds_write2_b32 v19, v21, v0 offset1:2
	s_waitcnt lgkmcnt(2)
	v_cndmask_b32_e64 v0, v23, v22, s[6:7]
	v_add_f32_e32 v0, v1, v0
	ds_bpermute_b32 v1, v102, v139
	s_waitcnt lgkmcnt(2)
	v_cndmask_b32_e64 v21, v20, v23, s[6:7]
	v_add_f32_e32 v2, v2, v21
	ds_bpermute_b32 v21, v102, v143
	ds_write2_b32 v19, v0, v2 offset0:4 offset1:6
	s_waitcnt lgkmcnt(2)
	v_cndmask_b32_e64 v0, v1, v20, s[6:7]
	v_add_f32_e32 v0, v3, v0
	ds_bpermute_b32 v2, v102, v83
	s_waitcnt lgkmcnt(2)
	v_cndmask_b32_e64 v1, v21, v1, s[6:7]
	ds_bpermute_b32 v3, v102, v147
	v_add_f32_e32 v1, v8, v1
	ds_write2_b32 v19, v0, v1 offset0:8 offset1:10
	ds_bpermute_b32 v1, v102, v59
	ds_bpermute_b32 v8, v102, v63
	s_waitcnt lgkmcnt(4)
	v_cndmask_b32_e64 v0, v2, v21, s[6:7]
	s_waitcnt lgkmcnt(3)
	v_cndmask_b32_e64 v2, v3, v2, s[6:7]
	v_add_f32_e32 v0, v9, v0
	v_add_f32_e32 v2, v10, v2
	ds_write2_b32 v19, v0, v2 offset0:12 offset1:14
	s_waitcnt lgkmcnt(2)
	v_cndmask_b32_e64 v0, v1, v3, s[6:7]
	ds_bpermute_b32 v2, v102, v51
	s_waitcnt lgkmcnt(2)
	v_cndmask_b32_e64 v1, v8, v1, s[6:7]
	ds_bpermute_b32 v3, v102, v55
	v_add_f32_e32 v0, v11, v0
	v_add_f32_e32 v1, v12, v1
	ds_write2_b32 v19, v0, v1 offset0:16 offset1:18
	ds_bpermute_b32 v1, v102, v43
	s_waitcnt lgkmcnt(3)
	v_cndmask_b32_e64 v0, v2, v8, s[6:7]
	s_waitcnt lgkmcnt(2)
	v_cndmask_b32_e64 v2, v3, v2, s[6:7]
	ds_bpermute_b32 v8, v102, v47
	v_add_f32_e32 v0, v13, v0
	v_add_f32_e32 v2, v14, v2
	ds_write2_b32 v19, v0, v2 offset0:20 offset1:22
	s_waitcnt lgkmcnt(2)
	v_cndmask_b32_e64 v0, v1, v3, s[6:7]
	ds_bpermute_b32 v2, v102, v37
	ds_bpermute_b32 v3, v102, v93
	s_waitcnt lgkmcnt(3)
	v_cndmask_b32_e64 v1, v8, v1, s[6:7]
	v_add_f32_e32 v0, v15, v0
	v_add_f32_e32 v1, v16, v1
	ds_write2_b32 v19, v0, v1 offset0:24 offset1:26
	s_waitcnt lgkmcnt(2)
	v_cndmask_b32_e64 v0, v2, v8, s[6:7]
	s_waitcnt lgkmcnt(1)
	v_cndmask_b32_e64 v1, v3, v2, s[6:7]
	v_lshl_add_u32 v112, v89, 3, 32
	v_add_f32_e32 v0, v17, v0
	v_add_f32_e32 v1, v18, v1
	v_mad_u32_u24 v20, v90, s5, v112
	ds_write2_b32 v19, v0, v1 offset0:28 offset1:30
	v_add_u32_e32 v89, 0x4800, v20
	ds_read2_b64 v[0:3], v89 offset1:2
	v_cvt_pk_bf16_f32 v16, v124, v125
	v_cvt_pk_bf16_f32 v17, v126, v127
	v_cvt_pk_bf16_f32 v18, v4, v5
	v_cvt_pk_bf16_f32 v19, v6, v7
	v_add_u32_e32 v91, 0x6800, v20
	ds_read2_b64 v[114:117], v89 offset0:4 offset1:6
	s_waitcnt lgkmcnt(1)
	v_mfma_f32_32x32x16_bf16 v[0:15], v[0:3], v[16:19], 0
	ds_read2_b64 v[20:23], v91 offset0:64 offset1:66
	v_cvt_pk_bf16_f32 v118, v128, v129
	v_cvt_pk_bf16_f32 v119, v130, v131
	v_cvt_pk_bf16_f32 v120, v132, v133
	v_cvt_pk_bf16_f32 v121, v134, v135
	v_cvt_pk_bf16_f32 v80, v80, v81
	v_cvt_pk_bf16_f32 v81, v82, v83
	s_waitcnt lgkmcnt(1)
	v_mfma_f32_32x32x16_bf16 v[0:15], v[114:117], v[118:121], v[0:15]
	ds_read2_b64 v[114:117], v91 offset0:68 offset1:70
	v_cvt_pk_bf16_f32 v82, v144, v145
	v_cvt_pk_bf16_f32 v83, v146, v147
	v_cvt_pk_bf16_f32 v56, v56, v57
	v_cvt_pk_bf16_f32 v57, v58, v59
	v_cvt_pk_bf16_f32 v58, v60, v61
	v_cvt_pk_bf16_f32 v59, v62, v63
	s_waitcnt lgkmcnt(1)
	v_mfma_f32_32x32x16_bf16 v[16:31], v[20:23], v[16:19], 0
	ds_read2_b64 v[60:63], v91 offset0:80 offset1:82
	v_cvt_pk_bf16_f32 v48, v48, v49
	v_cvt_pk_bf16_f32 v49, v50, v51
	v_cvt_pk_bf16_f32 v50, v52, v53
	v_cvt_pk_bf16_f32 v51, v54, v55
	ds_read2_b64 v[52:55], v91 offset0:84 offset1:86
	v_cvt_pk_bf16_f32 v40, v40, v41
	s_waitcnt lgkmcnt(2)
	v_mfma_f32_32x32x16_bf16 v[16:31], v[114:117], v[118:121], v[16:31]
	ds_read2_b64 v[114:117], v89 offset0:8 offset1:10
	v_cvt_pk_bf16_f32 v118, v136, v137
	v_cvt_pk_bf16_f32 v119, v138, v139
	v_cvt_pk_bf16_f32 v120, v140, v141
	v_cvt_pk_bf16_f32 v121, v142, v143
	v_cvt_pk_bf16_f32 v41, v42, v43
	v_cvt_pk_bf16_f32 v42, v44, v45
	s_waitcnt lgkmcnt(0)
; #define MFMA32(a, b, c) __builtin_amdgcn_mfma_f32_32x32x16_bf16((a), (b), (c), 0, 0, 0)
; DI void nsa_item(unsigned char* ws_, const float* qg, const bf16_t* proj, bf16_t* mix, int item, LP unsigned char* lds3) {
;     ...
;     f32x16 comb[2]; comb[0] = zero16(); comb[1] = zero16();
; #pragma unroll
;     for (int sub = 0; sub < 4; ++sub)
; #pragma unroll
;       for (int s2 = 0; s2 < 2; ++s2) {
;         const bf16x8 pb = pack8(x[sub][8 * s2], x[sub][8 * s2 + 1], x[sub][8 * s2 + 2], x[sub][8 * s2 + 3], x[sub][8 * s2 + 4], x[sub][8 * s2 + 5], x[sub][8 * s2 + 6], x[sub][8 * s2 + 7]);
; #pragma unroll
;         for (int dt = 0; dt < 2; ++dt) { const bf16_t* vp = VTs + (dt * 32 + r) * 136 + sub * 32 + 16 * s2 + 4 * hh;
;           const s16x4 lo = *(const s16x4*)vp, hi = *(const s16x4*)(vp + 8);
;           const bf16x8 va = __builtin_shufflevector(lo, hi, 0, 1, 2, 3, 4, 5, 6, 7);
;           comb[dt] = MFMA32(va, pb, comb[dt]); } }
; #pragma unroll
;     for (int i = 0; i < 16; ++i) { cmb[i * 512] = comb[0][i] * g0; cmb[(16 + i) * 512] = comb[1][i] * g0; }
;   }
;   if (tid < 64) msk[tid] = (qt < 16) ? ((qt == 31) ? 0xffffffffu : ((1u << (qt + 1)) - 1u)) : (1u | (1u << qt) | (1u << (qt - 1)));
	v_mfma_f32_32x32x16_bf16 v[0:15], v[114:117], v[118:121], v[0:15]
	ds_read2_b64 v[114:117], v91 offset0:72 offset1:74
	v_cvt_pk_bf16_f32 v43, v46, v47
	ds_read2_b64 v[44:47], v91 offset0:88 offset1:90
	v_mul_f32_e32 v32, v33, v32
	v_cvt_pk_bf16_f32 v34, v34, v35
	v_cvt_pk_bf16_f32 v35, v36, v37
	v_cvt_pk_bf16_f32 v36, v38, v39
	s_waitcnt lgkmcnt(1)
	v_mfma_f32_32x32x16_bf16 v[16:31], v[114:117], v[118:121], v[16:31]
	ds_read2_b64 v[114:117], v89 offset0:12 offset1:14
	v_cvt_pk_bf16_f32 v37, v32, v93
	v_lshl_add_u32 v32, v84, 2, 32
	v_div_fixup_f32 v33, v95, v92, 1.0
	v_add_u32_e32 v105, 0x11000, v32
	v_cmp_gt_i32_e32 vcc, 64, v84
	s_waitcnt lgkmcnt(0)
	v_mfma_f32_32x32x16_bf16 v[0:15], v[114:117], v[80:83], v[0:15]
	ds_read2_b64 v[114:117], v91 offset0:76 offset1:78
	s_waitcnt lgkmcnt(0)
	v_mfma_f32_32x32x16_bf16 v[16:31], v[114:117], v[80:83], v[16:31]
	ds_read2_b64 v[80:83], v89 offset0:16 offset1:18
	s_waitcnt lgkmcnt(0)
	v_mfma_f32_32x32x16_bf16 v[0:15], v[80:83], v[56:59], v[0:15]
	v_mfma_f32_32x32x16_bf16 v[16:31], v[60:63], v[56:59], v[16:31]
	ds_read2_b64 v[56:59], v89 offset0:20 offset1:22
	s_waitcnt lgkmcnt(0)
	v_mfma_f32_32x32x16_bf16 v[0:15], v[56:59], v[48:51], v[0:15]
	v_mfma_f32_32x32x16_bf16 v[16:31], v[52:55], v[48:51], v[16:31]
	ds_read2_b64 v[48:51], v89 offset0:24 offset1:26
	s_waitcnt lgkmcnt(0)
	v_mfma_f32_32x32x16_bf16 v[0:15], v[48:51], v[40:43], v[0:15]
	v_mfma_f32_32x32x16_bf16 v[16:31], v[44:47], v[40:43], v[16:31]
	ds_read2_b64 v[40:43], v89 offset0:28 offset1:30
	s_waitcnt lgkmcnt(0)
	v_mfma_f32_32x32x16_bf16 v[0:15], v[40:43], v[34:37], v[0:15]
	ds_read2_b64 v[38:41], v91 offset0:92 offset1:94
	s_waitcnt lgkmcnt(0)
	v_mfma_f32_32x32x16_bf16 v[16:31], v[38:41], v[34:37], v[16:31]
	s_nop 8
	v_mul_f32_e32 v0, v33, v0
	v_mul_f32_e32 v1, v33, v1
	ds_write2st64_b32 v105, v0, v1 offset1:8
	v_mul_f32_e32 v16, v33, v16
	v_mul_f32_e32 v0, v33, v17
	ds_write2st64_b32 v105, v16, v0 offset0:128 offset1:136
	v_mul_f32_e32 v0, v33, v2
	v_mul_f32_e32 v2, v33, v3
	v_mul_f32_e32 v1, v33, v18
	ds_write2st64_b32 v105, v0, v2 offset0:16 offset1:24
	v_mul_f32_e32 v0, v33, v19
	ds_write2st64_b32 v105, v1, v0 offset0:144 offset1:152
	v_mul_f32_e32 v0, v33, v4
	v_mul_f32_e32 v2, v33, v5
	v_mul_f32_e32 v1, v33, v20
	ds_write2st64_b32 v105, v0, v2 offset0:32 offset1:40
	v_mul_f32_e32 v0, v33, v21
	ds_write2st64_b32 v105, v1, v0 offset0:160 offset1:168
	v_mul_f32_e32 v0, v33, v6
	v_mul_f32_e32 v2, v33, v7
	v_mul_f32_e32 v1, v33, v22
	ds_write2st64_b32 v105, v0, v2 offset0:48 offset1:56
	v_mul_f32_e32 v0, v33, v23
	ds_write2st64_b32 v105, v1, v0 offset0:176 offset1:184
	v_mul_f32_e32 v0, v33, v8
	v_mul_f32_e32 v2, v33, v9
	v_mul_f32_e32 v1, v33, v24
	ds_write2st64_b32 v105, v0, v2 offset0:64 offset1:72
	v_mul_f32_e32 v0, v33, v25
	ds_write2st64_b32 v105, v1, v0 offset0:192 offset1:200
	v_mul_f32_e32 v0, v33, v10
	v_mul_f32_e32 v2, v33, v11
	v_mul_f32_e32 v1, v33, v26
	ds_write2st64_b32 v105, v0, v2 offset0:80 offset1:88
	v_mul_f32_e32 v0, v33, v27
	ds_write2st64_b32 v105, v1, v0 offset0:208 offset1:216
	v_mul_f32_e32 v0, v33, v12
	v_mul_f32_e32 v2, v33, v13
	v_mul_f32_e32 v1, v33, v28
	ds_write2st64_b32 v105, v0, v2 offset0:96 offset1:104
	v_mul_f32_e32 v0, v33, v29
	ds_write2st64_b32 v105, v1, v0 offset0:224 offset1:232
	v_mul_f32_e32 v0, v33, v14
	v_mul_f32_e32 v2, v33, v15
	v_mul_f32_e32 v1, v33, v30
	ds_write2st64_b32 v105, v0, v2 offset0:112 offset1:120
	v_mul_f32_e32 v0, v33, v31
	ds_write2st64_b32 v105, v1, v0 offset0:240 offset1:248
	s_and_saveexec_b64 s[2:3], vcc
	s_cbranch_execz .LBB0_403
	v_cmp_lt_u32_e32 vcc, 15, v100
	s_and_saveexec_b64 s[4:5], vcc
	s_xor_b64 s[4:5], exec, s[4:5]
	v_sub_u32_e32 v1, 30, v108
	v_lshlrev_b32_e64 v0, v100, 1
	v_lshlrev_b32_e64 v1, v1, 1
	v_or3_b32 v0, v0, v1, 1
	s_andn2_saveexec_b64 s[4:5], s[4:5]
	v_sub_u32_e32 v0, 32, v108
	v_lshlrev_b32_e64 v0, v0, -1
	v_not_b32_e32 v0, v0
	s_or_b64 exec, exec, s[4:5]
	v_add_u32_e32 v1, 0x10c00, v32
	ds_write_b32 v1, v0

; DI int crow(int reg, int h) { return (reg & 3) + 8 * (reg >> 2) + 4 * h; }
; #define MFMA32(a, b, c) __builtin_amdgcn_mfma_f32_32x32x16_bf16((a), (b), (c), 0, 0, 0)
; template <int MODE>
; DI void nsa_flash(const bf16_t* kbase, const bf16_t* vbase, int j0, int j1, int t, unsigned selmask, const bf16x8 (&qf)[4],
;                   f32x16 (&o)[2], float& lsum, bf16_t* Ks, bf16_t* VTs, int tid, int r, int hh) {
;     ...
;     __syncthreads();
;     *(u32x4*)(Ks + kkey * 72 + kdc * 8) = kreg;
; #pragma unroll
;     for (int e = 0; e < 4; ++e) { VTs[(dc * 8 + 2 * e) * 136 + key] = (bf16_t)(vreg[e] & 0xffffu); VTs[(dc * 8 + 2 * e + 1) * 136 + key] = (bf16_t)(vreg[e] >> 16); }
;     __syncthreads();
;     if (j < j1) { kreg = *(const u32x4*)(kbase + (size_t)((j + 1) * 64 + kkey) * LDP0 + kdc * 8); vreg = *(const u32x4*)(vbase + (size_t)((j + 1) * 64 + key) * LDP0 + dc * 8); }
;     const bool rowsel = (MODE == 1) ? (((selmask >> j) & 1u) != 0u) : true;
;     const bool needmask = (j == j1) || (MODE == 2 && j + 8 == j1);
;     f32x16 x[2]; float mx = NEGF;
; #pragma unroll
;     for (int sub = 0; sub < 2; ++sub) { x[sub] = zero16();
; #pragma unroll
;       for (int kk = 0; kk < 4; ++kk) x[sub] = MFMA32(*(const bf16x8*)(Ks + (sub * 32 + r) * 72 + kk * 16 + 8 * hh), qf[kk], x[sub]); }
;     if (needmask) {
; #pragma unroll
;       for (int sub = 0; sub < 2; ++sub)
; #pragma unroll
;         for (int i = 0; i < 16; ++i) { const int kp = j * 64 + sub * 32 + crow(i, hh);
;           bool ok = (kp <= t); if (MODE == 2) ok = ok && (t - kp < 512);
;           x[sub][i] = ok ? x[sub][i] : NEGF; }
;     }
; #pragma unroll
;     for (int sub = 0; sub < 2; ++sub)
; #pragma unroll
;       for (int i = 0; i < 16; ++i) mx = fmaxf(mx, x[sub][i]);
;     mx = fmaxf(mx, __shfl_xor(mx, 32));
;     mx = rowsel ? fmaxf(m, mx) : m;
.LBB0_634:
	s_or_b64 exec, exec, s[2:3]
	v_add_f32_e32 v32, 1.0, v119
	v_div_scale_f32 v33, s[2:3], v32, v32, 1.0
	v_rcp_f32_e32 v34, v33
	s_waitcnt lgkmcnt(0)
	s_barrier
	v_fma_f32 v35, -v33, v34, 1.0
	v_fmac_f32_e32 v34, v35, v34
	v_div_scale_f32 v35, vcc, 1.0, v32, 1.0
	v_mul_f32_e32 v36, v35, v34
	v_fma_f32 v37, -v33, v36, v35
	v_fmac_f32_e32 v36, v37, v34
	v_fma_f32 v33, -v33, v36, v35
	v_div_fmas_f32 v33, v33, v34, v36
	v_div_fixup_f32 v97, v33, v32, 1.0
	v_lshlrev_b32_e32 v32, 1, v128
	v_add_u32_e32 v33, v123, v32
	v_add3_u32 v32, 32, v32, v124
	s_waitcnt vmcnt(1)
	ds_write_b128 v125, v[84:87]
	s_waitcnt vmcnt(0)
	ds_write_b16 v117, v80 offset:18432
	ds_write_b16_d16_hi v118, v80 offset:18704
	ds_write_b16_d16_hi v32, v81 offset:18704
	v_lshlrev_b32_e32 v32, 1, v127
	ds_write_b16 v33, v81 offset:18432
	v_add_u32_e32 v33, v123, v32
	v_add3_u32 v32, 32, v32, v124
	ds_write_b16_d16_hi v32, v82 offset:18704
	v_lshlrev_b32_e32 v32, 1, v126
	ds_write_b16 v33, v82 offset:18432
	v_add_u32_e32 v33, v123, v32
	v_add3_u32 v32, 32, v32, v124
	v_add_u32_e32 v94, v111, v114
	ds_write_b16 v33, v83 offset:18432
	ds_write_b16_d16_hi v32, v83 offset:18704
	s_waitcnt lgkmcnt(0)
	s_barrier
	ds_read_b128 v[32:35], v94
	ds_read_b128 v[36:39], v94 offset:32
	s_waitcnt lgkmcnt(1)
	v_mfma_f32_32x32x16_bf16 v[48:63], v[32:35], v[64:67], 0
	ds_read_b128 v[32:35], v94 offset:64
	ds_read_b128 v[80:83], v94 offset:4640
	v_cmp_le_i32_e32 vcc, v104, v109
	s_mov_b32 s2, 0xf149f2ca
	s_waitcnt lgkmcnt(2)
	v_mfma_f32_32x32x16_bf16 v[48:63], v[36:39], v[68:71], v[48:63]
	s_waitcnt lgkmcnt(1)
	v_mfma_f32_32x32x16_bf16 v[48:63], v[32:35], v[72:75], v[48:63]
	ds_read_b128 v[32:35], v94 offset:96
	s_waitcnt lgkmcnt(0)
	v_mfma_f32_32x32x16_bf16 v[48:63], v[32:35], v[76:79], v[48:63]
	ds_read_b128 v[32:35], v94 offset:4608
	s_waitcnt lgkmcnt(0)
	v_mfma_f32_32x32x16_bf16 v[32:47], v[32:35], v[64:67], 0
	s_nop 8
	v_cndmask_b32_e32 v48, v201, v48, vcc
	v_cmp_lt_i32_e32 vcc, v104, v109
	s_nop 1
	v_cndmask_b32_e32 v49, v201, v49, vcc
	v_mfma_f32_32x32x16_bf16 v[32:47], v[80:83], v[68:71], v[32:47]
	ds_read_b128 v[80:83], v94 offset:4672
	s_waitcnt lgkmcnt(0)
	v_mfma_f32_32x32x16_bf16 v[32:47], v[80:83], v[72:75], v[32:47]
	ds_read_b128 v[80:83], v94 offset:4704
	s_waitcnt lgkmcnt(0)
	v_mfma_f32_32x32x16_bf16 v[32:47], v[80:83], v[76:79], v[32:47]
	v_or_b32_e32 v80, v104, v110
	v_or_b32_e32 v81, 2, v80
	v_cmp_le_i32_e32 vcc, v81, v101
	v_or_b32_e32 v81, 3, v80
	s_nop 0
	v_cndmask_b32_e32 v50, v201, v50, vcc
	v_cmp_le_i32_e32 vcc, v81, v101
	v_or_b32_e32 v81, 8, v80
	s_nop 0
	v_cndmask_b32_e32 v51, v201, v51, vcc
	v_cmp_le_i32_e32 vcc, v81, v101
	v_or_b32_e32 v81, 9, v80
	s_nop 0
	v_cndmask_b32_e32 v52, v201, v52, vcc
	v_cmp_le_i32_e32 vcc, v81, v101
	v_or_b32_e32 v81, 10, v80
	s_nop 0
	v_cndmask_b32_e32 v53, v201, v53, vcc
	v_cmp_le_i32_e32 vcc, v81, v101
	v_or_b32_e32 v81, 11, v80
	s_nop 0
	v_cndmask_b32_e32 v54, v201, v54, vcc
	v_cmp_le_i32_e32 vcc, v81, v101
	v_or_b32_e32 v81, 16, v80
	s_nop 0
	v_cndmask_b32_e32 v55, v201, v55, vcc
	v_cmp_le_i32_e32 vcc, v81, v101
	v_or_b32_e32 v81, 17, v80
	s_nop 0
	v_cndmask_b32_e32 v56, v201, v56, vcc
	v_cmp_le_i32_e32 vcc, v81, v101
	v_or_b32_e32 v81, 18, v80
	s_nop 0
	v_cndmask_b32_e32 v57, v201, v57, vcc
	v_cmp_le_i32_e32 vcc, v81, v101
	v_or_b32_e32 v81, 19, v80
	s_nop 0
	v_cndmask_b32_e32 v58, v201, v58, vcc
	v_cmp_le_i32_e32 vcc, v81, v101
	v_or_b32_e32 v81, 24, v80
	s_nop 0
	v_cndmask_b32_e32 v59, v201, v59, vcc
	v_cmp_le_i32_e32 vcc, v81, v101
	v_or_b32_e32 v81, 25, v80
	s_nop 0
	v_cndmask_b32_e32 v60, v201, v60, vcc
	v_cmp_le_i32_e32 vcc, v81, v101
	v_or_b32_e32 v81, 26, v80
	s_nop 0
	v_cndmask_b32_e32 v61, v201, v61, vcc
	v_cmp_le_i32_e32 vcc, v81, v101
	v_or_b32_e32 v81, 27, v80
	s_nop 0
	v_cndmask_b32_e32 v62, v201, v62, vcc
	v_cmp_le_i32_e32 vcc, v81, v101
	v_or_b32_e32 v81, 32, v80
	s_nop 0
	v_cndmask_b32_e32 v63, v201, v63, vcc
	v_cmp_le_i32_e32 vcc, v81, v101
	v_or_b32_e32 v81, 33, v80
	s_nop 0
	v_cndmask_b32_e32 v32, v201, v32, vcc
	v_cmp_le_i32_e32 vcc, v81, v101
	v_or_b32_e32 v81, 34, v80
	s_nop 0
	v_cndmask_b32_e32 v33, v201, v33, vcc
	v_cmp_le_i32_e32 vcc, v81, v101
	v_or_b32_e32 v81, 35, v80
	s_nop 0
	v_cndmask_b32_e32 v34, v201, v34, vcc
	v_cmp_le_i32_e32 vcc, v81, v101
	v_or_b32_e32 v81, 40, v80
	s_nop 0
	v_cndmask_b32_e32 v35, v201, v35, vcc
	v_cmp_le_i32_e32 vcc, v81, v101
	v_or_b32_e32 v81, 41, v80
	s_nop 0
	v_cndmask_b32_e32 v36, v201, v36, vcc
	v_cmp_le_i32_e32 vcc, v81, v101
	v_or_b32_e32 v81, 42, v80
	s_nop 0
	v_cndmask_b32_e32 v37, v201, v37, vcc
	v_cmp_le_i32_e32 vcc, v81, v101
	v_or_b32_e32 v81, 43, v80
	s_nop 0
	v_cndmask_b32_e32 v38, v201, v38, vcc
	v_cmp_le_i32_e32 vcc, v81, v101
	v_or_b32_e32 v81, 48, v80
	s_nop 0
	v_cndmask_b32_e32 v39, v201, v39, vcc
	v_cmp_le_i32_e32 vcc, v81, v101
	v_or_b32_e32 v81, 49, v80
	s_nop 0
	v_cndmask_b32_e32 v40, v201, v40, vcc
	v_cmp_le_i32_e32 vcc, v81, v101
	v_or_b32_e32 v81, 50, v80
	s_nop 0
	v_cndmask_b32_e32 v41, v201, v41, vcc
	v_cmp_le_i32_e32 vcc, v81, v101
	v_or_b32_e32 v81, 51, v80
	s_nop 0
	v_cndmask_b32_e32 v42, v201, v42, vcc
	v_cmp_le_i32_e32 vcc, v81, v101
	v_or_b32_e32 v81, 56, v80
	s_nop 0
	v_cndmask_b32_e32 v43, v201, v43, vcc
	v_cmp_le_i32_e32 vcc, v81, v101
	v_or_b32_e32 v81, 57, v80
	s_nop 0
	v_cndmask_b32_e32 v44, v201, v44, vcc
	v_cmp_le_i32_e32 vcc, v81, v101
	v_or_b32_e32 v81, 58, v80
	v_or_b32_e32 v80, 59, v80
	v_cndmask_b32_e32 v45, v201, v45, vcc
	v_cmp_le_i32_e32 vcc, v81, v101
	s_nop 1
	v_cndmask_b32_e32 v46, v201, v46, vcc
	v_cmp_le_i32_e32 vcc, v80, v101
	v_lshrrev_b32_e32 v80, v100, v122
	v_and_b32_e32 v80, 1, v80
	v_cndmask_b32_e32 v47, v201, v47, vcc
	v_cmp_eq_u32_e32 vcc, 1, v80
	v_max3_f32 v80, v48, s2, v49
	v_max3_f32 v80, v80, v50, v51
	v_max3_f32 v80, v80, v52, v53
	v_max3_f32 v80, v80, v54, v55
	v_max3_f32 v80, v80, v56, v57
	v_max3_f32 v80, v80, v58, v59
	v_max3_f32 v80, v80, v60, v61
	v_max3_f32 v80, v80, v62, v63
	v_max3_f32 v80, v80, v32, v33
	v_max3_f32 v80, v80, v34, v35
	v_max3_f32 v80, v80, v36, v37
	v_max3_f32 v80, v80, v38, v39
	v_max3_f32 v80, v80, v40, v41
	v_max3_f32 v80, v80, v42, v43
	v_max3_f32 v80, v80, v44, v45
	v_max3_f32 v80, v80, v46, v47
	v_mov_b32_e32 v81, v80
	s_waitcnt lgkmcnt(0)
; #define MFMA32(a, b, c) __builtin_amdgcn_mfma_f32_32x32x16_bf16((a), (b), (c), 0, 0, 0)
; template <int MODE>
; DI void nsa_flash(const bf16_t* kbase, const bf16_t* vbase, int j0, int j1, int t, unsigned selmask, const bf16x8 (&qf)[4],
;                   f32x16 (&o)[2], float& lsum, bf16_t* Ks, bf16_t* VTs, int tid, int r, int hh) {
;     ...
;     mx = fmaxf(mx, __shfl_xor(mx, 32));
;     mx = rowsel ? fmaxf(m, mx) : m;
;     const float alpha = __builtin_amdgcn_exp2f(m - mx); m = mx;
;     const float mexp = (rowsel && mx > -1e29f) ? mx : 1e30f;
;     float ps = 0.f;
; #pragma unroll
;     for (int sub = 0; sub < 2; ++sub)
; #pragma unroll
;       for (int i = 0; i < 16; ++i) { const float pv = __builtin_amdgcn_exp2f(x[sub][i] - mexp); x[sub][i] = pv; ps += pv; }
;     ps += __shfl_xor(ps, 32);
;     lsum = lsum * alpha + ps;
; #pragma unroll
;     for (int i = 0; i < 16; ++i) { o[0][i] *= alpha; o[1][i] *= alpha; }
; #pragma unroll
;     for (int sub = 0; sub < 2; ++sub)
; #pragma unroll
;       for (int s2 = 0; s2 < 2; ++s2) {
;         const bf16x8 pb = pack8(x[sub][8 * s2], x[sub][8 * s2 + 1], x[sub][8 * s2 + 2], x[sub][8 * s2 + 3], x[sub][8 * s2 + 4], x[sub][8 * s2 + 5], x[sub][8 * s2 + 6], x[sub][8 * s2 + 7]);
; #pragma unroll
;         for (int dt = 0; dt < 2; ++dt) { const bf16_t* vp = VTs + (dt * 32 + r) * 136 + sub * 32 + 16 * s2 + 4 * hh;
;           const s16x4 lo = *(const s16x4*)vp, hi = *(const s16x4*)(vp + 8);
;           const bf16x8 va = __builtin_shufflevector(lo, hi, 0, 1, 2, 3, 4, 5, 6, 7);
;           o[dt] = MFMA32(va, pb, o[dt]); } }
;   }
	s_nop 1
	v_permlane32_swap_b32_e32 v80, v81
	v_max3_f32 v80, v129, v80, v81
	v_cndmask_b32_e32 v81, v129, v80, vcc
	v_cmp_lt_f32_e64 s[6:7], s90, v81
	s_and_b64 vcc, vcc, s[6:7]
	v_cndmask_b32_e32 v80, v202, v80, vcc
	v_sub_f32_e32 v48, v48, v80
	v_sub_f32_e32 v82, v129, v81
	v_exp_f32_e32 v81, v48
	v_sub_f32_e32 v49, v49, v80
	v_exp_f32_e32 v83, v49
	v_sub_f32_e32 v49, v50, v80
	v_exp_f32_e32 v84, v49
	v_sub_f32_e32 v49, v51, v80
	v_exp_f32_e32 v51, v49
	v_sub_f32_e32 v49, v52, v80
	v_add_f32_e32 v48, 0, v81
	v_exp_f32_e32 v85, v49
	v_sub_f32_e32 v49, v53, v80
	v_add_f32_e32 v48, v83, v48
	v_exp_f32_e32 v53, v49
	v_sub_f32_e32 v49, v54, v80
	v_add_f32_e32 v48, v84, v48
	v_exp_f32_e32 v54, v49
	v_sub_f32_e32 v49, v55, v80
	v_add_f32_e32 v48, v51, v48
	v_exp_f32_e32 v55, v49
	v_sub_f32_e32 v49, v56, v80
	v_add_f32_e32 v48, v85, v48
	v_exp_f32_e32 v49, v49
	v_sub_f32_e32 v50, v57, v80
	v_add_f32_e32 v48, v53, v48
	v_exp_f32_e32 v50, v50
	v_sub_f32_e32 v52, v58, v80
	v_add_f32_e32 v48, v54, v48
	v_exp_f32_e32 v56, v52
	v_sub_f32_e32 v52, v59, v80
	v_add_f32_e32 v48, v55, v48
	v_exp_f32_e32 v57, v52
	v_sub_f32_e32 v52, v60, v80
	v_add_f32_e32 v48, v49, v48
	v_exp_f32_e32 v58, v52
	v_sub_f32_e32 v52, v61, v80
	v_add_f32_e32 v48, v50, v48
	v_exp_f32_e32 v59, v52
	v_sub_f32_e32 v52, v62, v80
	v_add_f32_e32 v48, v56, v48
	v_exp_f32_e32 v60, v52
	v_sub_f32_e32 v52, v63, v80
	v_add_f32_e32 v48, v57, v48
	v_exp_f32_e32 v61, v52
	v_sub_f32_e32 v32, v32, v80
	v_add_f32_e32 v48, v58, v48
	v_exp_f32_e32 v62, v32
	v_sub_f32_e32 v33, v33, v80
	v_add_f32_e32 v48, v59, v48
	v_exp_f32_e32 v63, v33
	v_sub_f32_e32 v33, v34, v80
	v_add_f32_e32 v48, v60, v48
	v_exp_f32_e32 v86, v33
	v_sub_f32_e32 v33, v35, v80
	v_add_f32_e32 v48, v61, v48
	v_exp_f32_e32 v87, v33
	v_sub_f32_e32 v33, v36, v80
	v_add_f32_e32 v32, v62, v48
	v_exp_f32_e32 v109, v33
	v_sub_f32_e32 v33, v37, v80
	v_add_f32_e32 v32, v63, v32
	v_exp_f32_e32 v110, v33
	v_sub_f32_e32 v33, v38, v80
	v_add_f32_e32 v32, v86, v32
	v_exp_f32_e32 v111, v33
	v_sub_f32_e32 v33, v39, v80
	v_add_f32_e32 v32, v87, v32
	v_exp_f32_e32 v114, v33
	v_sub_f32_e32 v33, v40, v80
	v_add_f32_e32 v32, v109, v32
	v_exp_f32_e32 v119, v33
	v_sub_f32_e32 v33, v41, v80
	v_add_f32_e32 v32, v110, v32
	v_exp_f32_e32 v122, v33
	v_sub_f32_e32 v33, v42, v80
	v_add_f32_e32 v32, v111, v32
	v_exp_f32_e32 v123, v33
	v_sub_f32_e32 v33, v43, v80
	v_add_f32_e32 v32, v114, v32
	v_exp_f32_e32 v124, v33
	v_sub_f32_e32 v33, v44, v80
	v_add_f32_e32 v32, v119, v32
	v_exp_f32_e32 v125, v33
	v_sub_f32_e32 v33, v45, v80
	v_add_f32_e32 v32, v122, v32
	v_exp_f32_e32 v126, v33
	v_sub_f32_e32 v33, v46, v80
	v_add_f32_e32 v32, v123, v32
	v_exp_f32_e32 v127, v33
	v_sub_f32_e32 v33, v47, v80
	v_add_f32_e32 v32, v124, v32
	v_exp_f32_e32 v80, v33
	v_add_f32_e32 v32, v125, v32
	v_exp_f32_e32 v52, v82
	v_add_f32_e32 v32, v126, v32
	v_add_f32_e32 v32, v127, v32
	v_add_f32_e32 v32, v80, v32
	ds_bpermute_b32 v33, v102, v32
	v_pk_mul_f32 v[44:45], v[12:13], v[52:53] op_sel_hi:[1,0]
	v_pk_mul_f32 v[12:13], v[28:29], v[52:53] op_sel_hi:[1,0]
	v_add_u32_e32 v28, v112, v113
	v_add_u32_e32 v95, 0x4800, v28
	v_pk_mul_f32 v[36:37], v[4:5], v[52:53] op_sel_hi:[1,0]
	v_pk_mul_f32 v[4:5], v[20:21], v[52:53] op_sel_hi:[1,0]
	v_pk_mul_f32 v[38:39], v[6:7], v[52:53] op_sel_hi:[1,0]
	v_pk_mul_f32 v[6:7], v[22:23], v[52:53] op_sel_hi:[1,0]
	v_pk_mul_f32 v[40:41], v[8:9], v[52:53] op_sel_hi:[1,0]
	v_pk_mul_f32 v[8:9], v[24:25], v[52:53] op_sel_hi:[1,0]
	v_pk_mul_f32 v[42:43], v[10:11], v[52:53] op_sel_hi:[1,0]
	v_pk_mul_f32 v[10:11], v[26:27], v[52:53] op_sel_hi:[1,0]
	ds_read2_b64 v[20:23], v95 offset1:2
	ds_read2_b64 v[24:27], v95 offset0:4 offset1:6
	s_waitcnt lgkmcnt(2)
	v_add_f32_e32 v48, v32, v33
	v_pk_mul_f32 v[32:33], v[0:1], v[52:53] op_sel_hi:[1,0]
	v_pk_mul_f32 v[0:1], v[16:17], v[52:53] op_sel_hi:[1,0]
	v_pk_mul_f32 v[34:35], v[2:3], v[52:53] op_sel_hi:[1,0]
	v_pk_mul_f32 v[2:3], v[18:19], v[52:53] op_sel_hi:[1,0]
	v_pk_mul_f32 v[46:47], v[14:15], v[52:53] op_sel_hi:[1,0]
	v_cvt_pk_bf16_f32 v16, v81, v83
	v_cvt_pk_bf16_f32 v17, v84, v51
	v_cvt_pk_bf16_f32 v18, v85, v53
	v_cvt_pk_bf16_f32 v19, v54, v55
	v_add_u32_e32 v96, 0x6800, v28
	v_pk_mul_f32 v[14:15], v[30:31], v[52:53] op_sel_hi:[1,0]
	s_waitcnt lgkmcnt(1)
	v_mfma_f32_32x32x16_bf16 v[32:47], v[20:23], v[16:19], v[32:47]
	ds_read2_b64 v[20:23], v96 offset0:64 offset1:66
	v_fmac_f32_e32 v48, v121, v52
	s_waitcnt lgkmcnt(0)
	v_mfma_f32_32x32x16_bf16 v[0:15], v[20:23], v[16:19], v[0:15]
	ds_read2_b64 v[20:23], v96 offset0:68 offset1:70
	v_cvt_pk_bf16_f32 v16, v49, v50
	v_cvt_pk_bf16_f32 v17, v56, v57
	v_cvt_pk_bf16_f32 v18, v58, v59
	v_cvt_pk_bf16_f32 v19, v60, v61
	ds_read2st64_b32 v[50:51], v105 offset0:96 offset1:104
	s_waitcnt lgkmcnt(1)
	v_mfma_f32_32x32x16_bf16 v[0:15], v[20:23], v[16:19], v[0:15]
	ds_read2_b64 v[20:23], v95 offset0:8 offset1:10
	v_mfma_f32_32x32x16_bf16 v[32:47], v[24:27], v[16:19], v[32:47]
	v_cvt_pk_bf16_f32 v16, v62, v63
	v_cvt_pk_bf16_f32 v17, v86, v87
	v_cvt_pk_bf16_f32 v18, v109, v110
	v_cvt_pk_bf16_f32 v19, v111, v114
	s_waitcnt lgkmcnt(0)
	s_nop 0
	v_mfma_f32_32x32x16_bf16 v[32:47], v[20:23], v[16:19], v[32:47]
	ds_read2_b64 v[20:23], v96 offset0:72 offset1:74
	s_waitcnt lgkmcnt(0)
	v_mfma_f32_32x32x16_bf16 v[0:15], v[20:23], v[16:19], v[0:15]
	ds_read2_b64 v[20:23], v95 offset0:12 offset1:14
	v_cvt_pk_bf16_f32 v16, v119, v122
	v_cvt_pk_bf16_f32 v17, v123, v124
	v_cvt_pk_bf16_f32 v18, v125, v126
	v_cvt_pk_bf16_f32 v19, v127, v80
	s_waitcnt lgkmcnt(0)
	s_nop 0
	v_mfma_f32_32x32x16_bf16 v[32:47], v[20:23], v[16:19], v[32:47]
	ds_read2_b64 v[20:23], v96 offset0:76 offset1:78
	s_waitcnt lgkmcnt(0)
; template <int MODE>
; DI void nsa_flash(const bf16_t* kbase, const bf16_t* vbase, int j0, int j1, int t, unsigned selmask, const bf16x8 (&qf)[4],
;                   f32x16 (&o)[2], float& lsum, bf16_t* Ks, bf16_t* VTs, int tid, int r, int hh) {
;   float m = NEGF; lsum = 0.f; o[0] = zero16(); o[1] = zero16();
;   const int key = tid & 63, dc = tid >> 6, kkey = tid >> 3, kdc = tid & 7;
;   u32x4 kreg = *(const u32x4*)(kbase + (size_t)(j0 * 64 + kkey) * LDP0 + kdc * 8);
;   u32x4 vreg = *(const u32x4*)(vbase + (size_t)(j0 * 64 + key) * LDP0 + dc * 8);
; DI void nsa_item(unsigned char* ws_, const float* qg, const bf16_t* proj, bf16_t* mix, int item, LP unsigned char* lds3) {
;     ...
;   { const float sc = g1 / lsum;
; #pragma unroll
;     for (int i = 0; i < 16; ++i) { cmb[i * 512] += o[0][i] * sc; cmb[(16 + i) * 512] += o[1][i] * sc; } }
;   nsa_flash<2>(proj + (size_t)b * 2048 * LDP0 + N_KW + g * 64, proj + (size_t)b * 2048 * LDP0 + N_VW + g * 64, qt >= 8 ? qt - 8 : 0, qt, t, 0u, qf, o, lsum, Ks, VTs, tid, r, hh);
	v_mfma_f32_32x32x16_bf16 v[0:15], v[20:23], v[16:19], v[0:15]
	v_div_scale_f32 v16, s[2:3], v48, v48, v97
	v_rcp_f32_e32 v17, v16
	s_nop 0
	v_fma_f32 v18, -v16, v17, 1.0
	v_fmac_f32_e32 v17, v18, v17
	v_div_scale_f32 v18, vcc, v97, v48, v97
	v_mul_f32_e32 v19, v18, v17
	v_fma_f32 v20, -v16, v19, v18
	v_fmac_f32_e32 v19, v20, v17
	ds_read2st64_b32 v[20:21], v105 offset0:128 offset1:136
	v_fma_f32 v16, -v16, v19, v18
	v_div_fmas_f32 v16, v16, v17, v19
	v_div_fixup_f32 v16, v16, v48, v97
	ds_read2st64_b32 v[18:19], v105 offset1:8
	s_waitcnt lgkmcnt(1)
	v_fma_f32 v0, v0, v16, v20
	v_fmac_f32_e32 v21, v1, v16
	ds_write2st64_b32 v105, v0, v21 offset0:128 offset1:136
	ds_read2st64_b32 v[0:1], v105 offset0:16 offset1:24
	s_waitcnt lgkmcnt(2)
	v_fma_f32 v17, v32, v16, v18
	v_fmac_f32_e32 v19, v33, v16
	ds_write2st64_b32 v105, v17, v19 offset1:8
	ds_read2st64_b32 v[18:19], v105 offset0:144 offset1:152
	s_waitcnt lgkmcnt(2)
	v_fma_f32 v0, v34, v16, v0
	v_fmac_f32_e32 v1, v35, v16
	ds_write2st64_b32 v105, v0, v1 offset0:16 offset1:24
	ds_read2st64_b32 v[0:1], v105 offset0:32 offset1:40
	s_waitcnt lgkmcnt(2)
	v_fma_f32 v2, v2, v16, v18
	v_fmac_f32_e32 v19, v3, v16
	ds_write2st64_b32 v105, v2, v19 offset0:144 offset1:152
	ds_read2st64_b32 v[2:3], v105 offset0:160 offset1:168
	s_waitcnt lgkmcnt(2)
	v_fma_f32 v0, v36, v16, v0
	v_fmac_f32_e32 v1, v37, v16
	ds_read2st64_b32 v[36:37], v105 offset0:48 offset1:56
	ds_write2st64_b32 v105, v0, v1 offset0:32 offset1:40
	s_waitcnt lgkmcnt(2)
	v_fma_f32 v2, v4, v16, v2
	v_fmac_f32_e32 v3, v5, v16
	ds_write2st64_b32 v105, v2, v3 offset0:160 offset1:168
	s_waitcnt lgkmcnt(2)
	v_fma_f32 v2, v38, v16, v36
	v_fmac_f32_e32 v37, v39, v16
	ds_read2st64_b32 v[0:1], v105 offset0:176 offset1:184
	ds_write2st64_b32 v105, v2, v37 offset0:48 offset1:56
	ds_read2st64_b32 v[2:3], v105 offset0:64 offset1:72
	ds_read2st64_b32 v[38:39], v105 offset0:208 offset1:216
	ds_read2st64_b32 v[48:49], v105 offset0:224 offset1:232
	s_waitcnt lgkmcnt(4)
	v_fmac_f32_e32 v0, v6, v16
	v_mov_b32_e32 v6, v40
	s_waitcnt lgkmcnt(2)
	v_mov_b32_e32 v4, v2
	v_mov_b32_e32 v5, v1
	v_pk_fma_f32 v[32:33], v[6:7], v[16:17], v[4:5] op_sel_hi:[1,0,1]
	ds_write2st64_b32 v105, v0, v33 offset0:176 offset1:184
	ds_read2st64_b32 v[0:1], v105 offset0:192 offset1:200
	v_pk_mov_b32 v[4:5], v[40:41], v[8:9] op_sel:[1,0]
	v_mov_b32_e32 v2, v3
	v_mov_b32_e32 v8, v42
	v_cmp_lt_u32_e32 vcc, 7, v100
	s_waitcnt lgkmcnt(0)
	v_mov_b32_e32 v3, v0
	v_pk_fma_f32 v[34:35], v[4:5], v[16:17], v[2:3] op_sel_hi:[1,0,1]
	ds_read2st64_b32 v[2:3], v105 offset0:80 offset1:88
	v_fmac_f32_e32 v39, v11, v16
	v_fma_f32 v50, v44, v16, v50
	v_fma_f32 v48, v12, v16, v48
	v_fmac_f32_e32 v51, v45, v16
	s_waitcnt lgkmcnt(0)
	v_mov_b32_e32 v0, v2
	v_pk_fma_f32 v[40:41], v[8:9], v[16:17], v[0:1] op_sel_hi:[1,0,1]
	v_pk_mov_b32 v[0:1], v[42:43], v[10:11] op_sel:[1,0]
	v_mov_b32_e32 v2, v3
	v_mov_b32_e32 v3, v38
	v_pk_fma_f32 v[42:43], v[0:1], v[16:17], v[2:3] op_sel_hi:[1,0,1]
	ds_read2st64_b32 v[0:1], v105 offset0:112 offset1:120
	ds_read2st64_b32 v[2:3], v105 offset0:240 offset1:248
	v_fmac_f32_e32 v49, v13, v16
	ds_write2st64_b32 v105, v32, v34 offset0:64 offset1:72
	ds_write2st64_b32 v105, v35, v41 offset0:192 offset1:200
	s_waitcnt lgkmcnt(3)
	v_fma_f32 v0, v46, v16, v0
	v_fmac_f32_e32 v1, v47, v16
	ds_write2st64_b32 v105, v0, v1 offset0:112 offset1:120
	v_sub_u32_e32 v0, 23, v108
	v_cndmask_b32_e32 v97, 0, v0, vcc
	s_waitcnt lgkmcnt(3)
	v_fma_f32 v2, v14, v16, v2
	v_fmac_f32_e32 v3, v15, v16
	v_cmp_le_i32_e32 vcc, v97, v100
	ds_write2st64_b32 v105, v40, v42 offset0:80 offset1:88
	ds_write2st64_b32 v105, v43, v39 offset0:208 offset1:216
	ds_write2st64_b32 v105, v50, v51 offset0:96 offset1:104
	ds_write2st64_b32 v105, v48, v49 offset0:224 offset1:232
	ds_write2st64_b32 v105, v2, v3 offset0:240 offset1:248
	s_and_saveexec_b64 s[2:3], vcc
	s_xor_b64 s[10:11], exec, s[2:3]
	s_cbranch_execz .LBB0_642
	v_lshlrev_b32_e32 v0, 6, v107
	v_lshlrev_b32_e32 v0, 1, v0
	v_mov_b32_e32 v1, v169
	v_lshlrev_b32_e32 v107, 6, v97
	v_lshl_add_u64 v[0:1], v[90:91], 0, v[0:1]
	s_mov_b64 s[2:3], 0x2820
	v_or_b32_e32 v6, v120, v107
	v_lshl_add_u64 v[2:3], v[0:1], 0, s[2:3]
	s_mov_b64 s[2:3], 0x2a20
	v_mul_lo_u32 v6, v6, s97
	v_lshl_add_u64 v[0:1], v[0:1], 0, s[2:3]
	v_ashrrev_i32_e32 v7, 31, v6
	v_lshlrev_b64 v[4:5], 1, v[92:93]
	v_lshl_add_u64 v[6:7], v[0:1], 0, v[6:7]
	v_add_u32_e32 v8, v106, v107
	v_lshl_add_u64 v[6:7], v[6:7], 0, v[4:5]
	v_mad_i64_i32 v[8:9], s[2:3], v8, s97, v[2:3]
	v_lshl_add_u64 v[8:9], v[8:9], 0, v[168:169]
	global_load_dwordx4 v[84:87], v[6:7], off
	global_load_dwordx4 v[80:83], v[8:9], off
	v_mov_b32_e32 v110, 0
	v_lshl_add_u64 v[90:91], v[2:3], 0, v[168:169]
	v_lshl_add_u64 v[92:93], v[0:1], 0, v[4:5]
	v_add_u32_e32 v106, 0xfffffe00, v101
	v_add_u32_e32 v108, -8, v100
	v_mov_b32_e32 v111, 0xf149f2ca
	s_mov_b64 s[12:13], 0
	v_mov_b32_e32 v0, 0
	v_mov_b32_e32 v1, v110
	v_mov_b32_e32 v2, v110
	v_mov_b32_e32 v3, v110
	v_mov_b32_e32 v4, v110
	v_mov_b32_e32 v5, v110
	v_mov_b32_e32 v6, v110
	v_mov_b32_e32 v7, v110
	v_mov_b32_e32 v8, v110
	v_mov_b32_e32 v9, v110
	v_mov_b32_e32 v10, v110
	v_mov_b32_e32 v11, v110
	v_mov_b32_e32 v12, v110
	v_mov_b32_e32 v13, v110
	v_mov_b32_e32 v14, v110
	v_mov_b32_e32 v15, v110
	v_mov_b32_e32 v16, 0
	v_mov_b32_e32 v17, v110
	v_mov_b32_e32 v18, v110
	v_mov_b32_e32 v19, v110
	v_mov_b32_e32 v20, v110
	v_mov_b32_e32 v21, v110
	v_mov_b32_e32 v22, v110
	v_mov_b32_e32 v23, v110
	v_mov_b32_e32 v24, v110
	v_mov_b32_e32 v25, v110
	v_mov_b32_e32 v26, v110
	v_mov_b32_e32 v27, v110
	v_mov_b32_e32 v28, v110
	v_mov_b32_e32 v29, v110
	v_mov_b32_e32 v30, v110
	v_mov_b32_e32 v31, v110
	s_branch .LBB0_637
